# 64-byte alignment of hot loop heads (on top of v5)
# baseline (speedup 1.0000x reference)
; template <class Epi, class Sched, bool ALIGN_EPI = false, bool SP2 = false, bool F16 = false, bool TOKPERM = false>
; __device__ __forceinline__ void gemm_phase(PG8_LAS unsigned char* lds, const Gemm g, const Sched& S, const Epi& E, int wv) {
;     ...
;         const bool has_next = S.next(ui + 1, nxt);
;         const char* nA = has_next ? (const char*)g.A + (size_t)nxt.pm * tstep : cA; const char* nB = has_next ? (const char*)g.Bt + (size_t)nxt.pn * tstep : cB;
;     ...
; #pragma unroll
;         for (int a = 0; a < 2; ++a)
; #pragma unroll
;             for (int b = 0; b < 2; ++b)
; #pragma unroll
;                 for (int m = 0; m < 4; ++m)
; #pragma unroll
;                     for (int n = 0; n < 2; ++n) acc[a][b][m][n] = (f32x4){0.f, 0.f, 0.f, 0.f};
.LBB0_180:
	s_ashr_i32 s51, s50, 31
	s_lshl_b64 s[52:53], s[50:51], 19
	s_add_u32 s52, s40, s52
	s_addc_u32 s53, s41, s53
	s_and_b64 s[54:55], s[2:3], exec
	s_cselect_b32 s51, s53, s7
	s_cselect_b32 s77, s52, s6
	s_ashr_i32 s49, s48, 31
	s_lshl_b64 s[54:55], s[48:49], 19
	s_add_u32 s54, s33, s54
	s_addc_u32 s55, s36, s55
	s_and_b64 s[56:57], s[2:3], exec
	s_cselect_b32 s49, s55, s9
	s_cselect_b32 s78, s54, s8
	s_add_u32 s6, s6, 0x40080
	s_addc_u32 s7, s7, 0
	s_add_u32 s79, s8, 0x100
	v_mov_b32_e32 v0, 0
	s_addc_u32 s80, s9, 0
	s_mov_b32 s81, -2
	v_mov_b32_e32 v1, v0
	v_mov_b32_e32 v2, v0
	v_mov_b32_e32 v3, v0
	v_mov_b32_e32 v4, v0
	v_mov_b32_e32 v5, v0
	v_mov_b32_e32 v6, v0
	v_mov_b32_e32 v7, v0
	v_mov_b32_e32 v16, v0
	v_mov_b32_e32 v17, v0
	v_mov_b32_e32 v18, v0
	v_mov_b32_e32 v19, v0
	v_mov_b32_e32 v20, v0
	v_mov_b32_e32 v21, v0
	v_mov_b32_e32 v22, v0
	v_mov_b32_e32 v23, v0
	v_mov_b32_e32 v32, v0
	v_mov_b32_e32 v33, v0
	v_mov_b32_e32 v34, v0
	v_mov_b32_e32 v35, v0
	v_mov_b32_e32 v36, v0
	v_mov_b32_e32 v37, v0
	v_mov_b32_e32 v38, v0
	v_mov_b32_e32 v39, v0
	v_mov_b32_e32 v48, v0
	v_mov_b32_e32 v49, v0
	v_mov_b32_e32 v50, v0
	v_mov_b32_e32 v51, v0
	v_mov_b32_e32 v52, v0
	v_mov_b32_e32 v53, v0
	v_mov_b32_e32 v54, v0
	v_mov_b32_e32 v55, v0
	v_mov_b32_e32 v8, v0
	v_mov_b32_e32 v9, v0
	v_mov_b32_e32 v10, v0
	v_mov_b32_e32 v11, v0
	v_mov_b32_e32 v12, v0
	v_mov_b32_e32 v13, v0
	v_mov_b32_e32 v14, v0
	v_mov_b32_e32 v15, v0
	v_mov_b32_e32 v24, v0
	v_mov_b32_e32 v25, v0
	v_mov_b32_e32 v26, v0
	v_mov_b32_e32 v27, v0
	v_mov_b32_e32 v28, v0
	v_mov_b32_e32 v29, v0
	v_mov_b32_e32 v30, v0
	v_mov_b32_e32 v31, v0
	v_mov_b32_e32 v40, v0
	v_mov_b32_e32 v41, v0
	v_mov_b32_e32 v42, v0
	v_mov_b32_e32 v43, v0
	v_mov_b32_e32 v44, v0
	v_mov_b32_e32 v45, v0
	v_mov_b32_e32 v46, v0
	v_mov_b32_e32 v47, v0
	v_mov_b32_e32 v56, v0
	v_mov_b32_e32 v57, v0
	v_mov_b32_e32 v58, v0
	v_mov_b32_e32 v59, v0
	v_mov_b32_e32 v60, v0
	v_mov_b32_e32 v61, v0
	v_mov_b32_e32 v62, v0
	v_mov_b32_e32 v63, v0
	v_mov_b32_e32 v64, v0
	v_mov_b32_e32 v65, v0
	v_mov_b32_e32 v66, v0
	v_mov_b32_e32 v67, v0
	v_mov_b32_e32 v68, v0
	v_mov_b32_e32 v69, v0
	v_mov_b32_e32 v70, v0
	v_mov_b32_e32 v71, v0
	v_mov_b32_e32 v80, v0
	v_mov_b32_e32 v81, v0
	v_mov_b32_e32 v82, v0
	v_mov_b32_e32 v83, v0
	v_mov_b32_e32 v84, v0
	v_mov_b32_e32 v85, v0
	v_mov_b32_e32 v86, v0
	v_mov_b32_e32 v87, v0
	v_mov_b32_e32 v96, v0
	v_mov_b32_e32 v97, v0
	v_mov_b32_e32 v98, v0
	v_mov_b32_e32 v99, v0
	v_mov_b32_e32 v100, v0
	v_mov_b32_e32 v101, v0
	v_mov_b32_e32 v102, v0
	v_mov_b32_e32 v103, v0
	v_mov_b32_e32 v112, v0
	v_mov_b32_e32 v113, v0
	v_mov_b32_e32 v114, v0
	v_mov_b32_e32 v115, v0
	v_mov_b32_e32 v120, v0
	v_mov_b32_e32 v121, v0
	v_mov_b32_e32 v122, v0
	v_mov_b32_e32 v123, v0
	v_mov_b32_e32 v72, v0
	v_mov_b32_e32 v73, v0
	v_mov_b32_e32 v74, v0
	v_mov_b32_e32 v75, v0
	v_mov_b32_e32 v76, v0
	v_mov_b32_e32 v77, v0
	v_mov_b32_e32 v78, v0
	v_mov_b32_e32 v79, v0
	v_mov_b32_e32 v88, v0
	v_mov_b32_e32 v89, v0
	v_mov_b32_e32 v90, v0
	v_mov_b32_e32 v91, v0
	v_mov_b32_e32 v92, v0
	v_mov_b32_e32 v93, v0
	v_mov_b32_e32 v94, v0
	v_mov_b32_e32 v95, v0
	v_mov_b32_e32 v104, v0
	v_mov_b32_e32 v105, v0
	v_mov_b32_e32 v106, v0
	v_mov_b32_e32 v107, v0
	v_mov_b32_e32 v108, v0
	v_mov_b32_e32 v109, v0
	v_mov_b32_e32 v110, v0
	v_mov_b32_e32 v111, v0
	v_mov_b32_e32 v116, v0
	v_mov_b32_e32 v117, v0
	v_mov_b32_e32 v118, v0
	v_mov_b32_e32 v119, v0
	v_mov_b32_e32 v124, v0
	v_mov_b32_e32 v125, v0
	v_mov_b32_e32 v126, v0
	v_mov_b32_e32 v127, v0
	.p2align 6

; template <class Epi, class Sched, bool ALIGN_EPI = false, bool SP2 = false, bool F16 = false, bool TOKPERM = false>
; __device__ __forceinline__ void gemm_phase(PG8_LAS unsigned char* lds, const Gemm g, const Sched& S, const Epi& E, int wv) {
;     ...
; #pragma unroll
;         for (int a = 0; a < 2; ++a)
; #pragma unroll
;             for (int b = 0; b < 2; ++b)
; #pragma unroll
;                 for (int m = 0; m < 4; ++m)
; #pragma unroll
;                     for (int n = 0; n < 2; ++n) acc[a][b][m][n] = (f32x4){0.f, 0.f, 0.f, 0.f};
.LBB0_296:
	s_add_u32 s68, s18, 0x100
	v_mov_b32_e32 v0, 0
	s_addc_u32 s69, s19, 0
	s_mov_b32 s70, -2
	s_waitcnt lgkmcnt(0)
	v_mov_b32_e32 v1, v0
	v_mov_b32_e32 v2, v0
	v_mov_b32_e32 v3, v0
	v_mov_b32_e32 v4, v0
	v_mov_b32_e32 v5, v0
	v_mov_b32_e32 v6, v0
	v_mov_b32_e32 v7, v0
	v_mov_b32_e32 v16, v0
	v_mov_b32_e32 v17, v0
	v_mov_b32_e32 v18, v0
	v_mov_b32_e32 v19, v0
	v_mov_b32_e32 v20, v0
	v_mov_b32_e32 v21, v0
	v_mov_b32_e32 v22, v0
	v_mov_b32_e32 v23, v0
	v_mov_b32_e32 v32, v0
	v_mov_b32_e32 v33, v0
	v_mov_b32_e32 v34, v0
	v_mov_b32_e32 v35, v0
	v_mov_b32_e32 v36, v0
	v_mov_b32_e32 v37, v0
	v_mov_b32_e32 v38, v0
	v_mov_b32_e32 v39, v0
	v_mov_b32_e32 v48, v0
	v_mov_b32_e32 v49, v0
	v_mov_b32_e32 v50, v0
	v_mov_b32_e32 v51, v0
	v_mov_b32_e32 v52, v0
	v_mov_b32_e32 v53, v0
	v_mov_b32_e32 v54, v0
	v_mov_b32_e32 v55, v0
	v_mov_b32_e32 v8, v0
	v_mov_b32_e32 v9, v0
	v_mov_b32_e32 v10, v0
	v_mov_b32_e32 v11, v0
	v_mov_b32_e32 v12, v0
	v_mov_b32_e32 v13, v0
	v_mov_b32_e32 v14, v0
	v_mov_b32_e32 v15, v0
	v_mov_b32_e32 v24, v0
	v_mov_b32_e32 v25, v0
	v_mov_b32_e32 v26, v0
	v_mov_b32_e32 v27, v0
	v_mov_b32_e32 v28, v0
	v_mov_b32_e32 v29, v0
	v_mov_b32_e32 v30, v0
	v_mov_b32_e32 v31, v0
	v_mov_b32_e32 v40, v0
	v_mov_b32_e32 v41, v0
	v_mov_b32_e32 v42, v0
	v_mov_b32_e32 v43, v0
	v_mov_b32_e32 v44, v0
	v_mov_b32_e32 v45, v0
	v_mov_b32_e32 v46, v0
	v_mov_b32_e32 v47, v0
	v_mov_b32_e32 v56, v0
	v_mov_b32_e32 v57, v0
	v_mov_b32_e32 v58, v0
	v_mov_b32_e32 v59, v0
	v_mov_b32_e32 v60, v0
	v_mov_b32_e32 v61, v0
	v_mov_b32_e32 v62, v0
	v_mov_b32_e32 v63, v0
	v_mov_b32_e32 v64, v0
	v_mov_b32_e32 v65, v0
	v_mov_b32_e32 v66, v0
	v_mov_b32_e32 v67, v0
	v_mov_b32_e32 v68, v0
	v_mov_b32_e32 v69, v0
	v_mov_b32_e32 v70, v0
	v_mov_b32_e32 v71, v0
	v_mov_b32_e32 v80, v0
	v_mov_b32_e32 v81, v0
	v_mov_b32_e32 v82, v0
	v_mov_b32_e32 v83, v0
	v_mov_b32_e32 v84, v0
	v_mov_b32_e32 v85, v0
	v_mov_b32_e32 v86, v0
	v_mov_b32_e32 v87, v0
	v_mov_b32_e32 v96, v0
	v_mov_b32_e32 v97, v0
	v_mov_b32_e32 v98, v0
	v_mov_b32_e32 v99, v0
	v_mov_b32_e32 v100, v0
	v_mov_b32_e32 v101, v0
	v_mov_b32_e32 v102, v0
	v_mov_b32_e32 v103, v0
	v_mov_b32_e32 v112, v0
	v_mov_b32_e32 v113, v0
	v_mov_b32_e32 v114, v0
	v_mov_b32_e32 v115, v0
	v_mov_b32_e32 v116, v0
	v_mov_b32_e32 v117, v0
	v_mov_b32_e32 v118, v0
	v_mov_b32_e32 v119, v0
	v_mov_b32_e32 v72, v0
	v_mov_b32_e32 v73, v0
	v_mov_b32_e32 v74, v0
	v_mov_b32_e32 v75, v0
	v_mov_b32_e32 v76, v0
	v_mov_b32_e32 v77, v0
	v_mov_b32_e32 v78, v0
	v_mov_b32_e32 v79, v0
	v_mov_b32_e32 v88, v0
	v_mov_b32_e32 v89, v0
	v_mov_b32_e32 v90, v0
	v_mov_b32_e32 v91, v0
	v_mov_b32_e32 v92, v0
	v_mov_b32_e32 v93, v0
	v_mov_b32_e32 v94, v0
	v_mov_b32_e32 v95, v0
	v_mov_b32_e32 v104, v0
	v_mov_b32_e32 v105, v0
	v_mov_b32_e32 v106, v0
	v_mov_b32_e32 v107, v0
	v_mov_b32_e32 v108, v0
	v_mov_b32_e32 v109, v0
	v_mov_b32_e32 v110, v0
	v_mov_b32_e32 v111, v0
	v_mov_b32_e32 v120, v0
	v_mov_b32_e32 v121, v0
	v_mov_b32_e32 v122, v0
	v_mov_b32_e32 v123, v0
	v_mov_b32_e32 v124, v0
	v_mov_b32_e32 v125, v0
	v_mov_b32_e32 v126, v0
	v_mov_b32_e32 v127, v0
	.p2align 6

; template <class Epi, class Sched, bool ALIGN_EPI = false, bool SP2 = false, bool F16 = false, bool TOKPERM = false>
; __device__ __forceinline__ void gemm_phase(PG8_LAS unsigned char* lds, const Gemm g, const Sched& S, const Epi& E, int wv) {
;     ...
;         const bool has_next = S.next(ui + 1, nxt);
;         const char* nA = has_next ? (const char*)g.A + (size_t)nxt.pm * tstep : cA; const char* nB = has_next ? (const char*)g.Bt + (size_t)nxt.pn * tstep : cB;
;     ...
; #pragma unroll
;         for (int a = 0; a < 2; ++a)
; #pragma unroll
;             for (int b = 0; b < 2; ++b)
; #pragma unroll
;                 for (int m = 0; m < 4; ++m)
; #pragma unroll
;                     for (int n = 0; n < 2; ++n) acc[a][b][m][n] = (f32x4){0.f, 0.f, 0.f, 0.f};
.LBB0_381:
	s_ashr_i32 s71, s70, 31
	s_lshl_b64 s[10:11], s[70:71], 19
	s_add_u32 s72, s40, s10
	s_addc_u32 s73, s41, s11
	s_and_b64 s[10:11], s[4:5], exec
	s_cselect_b32 s12, s73, s7
	s_cselect_b32 s13, s72, s6
	s_ashr_i32 s69, s68, 31
	s_lshl_b64 s[10:11], s[68:69], 19
	s_add_u32 s74, s46, s10
	s_addc_u32 s75, s47, s11
	s_and_b64 s[10:11], s[4:5], exec
	s_cselect_b32 s59, s75, s9
	s_cselect_b32 s64, s74, s8
	s_add_u32 s6, s6, 0x40080
	s_addc_u32 s7, s7, 0
	s_add_u32 s69, s8, 0x100
	v_mov_b32_e32 v0, 0
	s_addc_u32 s71, s9, 0
	s_mov_b32 s76, -2
	s_waitcnt lgkmcnt(0)
	v_mov_b32_e32 v1, v0
	v_mov_b32_e32 v2, v0
	v_mov_b32_e32 v3, v0
	v_mov_b32_e32 v4, v0
	v_mov_b32_e32 v5, v0
	v_mov_b32_e32 v6, v0
	v_mov_b32_e32 v7, v0
	v_mov_b32_e32 v16, v0
	v_mov_b32_e32 v17, v0
	v_mov_b32_e32 v18, v0
	v_mov_b32_e32 v19, v0
	v_mov_b32_e32 v20, v0
	v_mov_b32_e32 v21, v0
	v_mov_b32_e32 v22, v0
	v_mov_b32_e32 v23, v0
	v_mov_b32_e32 v32, v0
	v_mov_b32_e32 v33, v0
	v_mov_b32_e32 v34, v0
	v_mov_b32_e32 v35, v0
	v_mov_b32_e32 v36, v0
	v_mov_b32_e32 v37, v0
	v_mov_b32_e32 v38, v0
	v_mov_b32_e32 v39, v0
	v_mov_b32_e32 v48, v0
	v_mov_b32_e32 v49, v0
	v_mov_b32_e32 v50, v0
	v_mov_b32_e32 v51, v0
	v_mov_b32_e32 v52, v0
	v_mov_b32_e32 v53, v0
	v_mov_b32_e32 v54, v0
	v_mov_b32_e32 v55, v0
	v_mov_b32_e32 v8, v0
	v_mov_b32_e32 v9, v0
	v_mov_b32_e32 v10, v0
	v_mov_b32_e32 v11, v0
	v_mov_b32_e32 v12, v0
	v_mov_b32_e32 v13, v0
	v_mov_b32_e32 v14, v0
	v_mov_b32_e32 v15, v0
	v_mov_b32_e32 v24, v0
	v_mov_b32_e32 v25, v0
	v_mov_b32_e32 v26, v0
	v_mov_b32_e32 v27, v0
	v_mov_b32_e32 v28, v0
	v_mov_b32_e32 v29, v0
	v_mov_b32_e32 v30, v0
	v_mov_b32_e32 v31, v0
	v_mov_b32_e32 v40, v0
	v_mov_b32_e32 v41, v0
	v_mov_b32_e32 v42, v0
	v_mov_b32_e32 v43, v0
	v_mov_b32_e32 v44, v0
	v_mov_b32_e32 v45, v0
	v_mov_b32_e32 v46, v0
	v_mov_b32_e32 v47, v0
	v_mov_b32_e32 v56, v0
	v_mov_b32_e32 v57, v0
	v_mov_b32_e32 v58, v0
	v_mov_b32_e32 v59, v0
	v_mov_b32_e32 v60, v0
	v_mov_b32_e32 v61, v0
	v_mov_b32_e32 v62, v0
	v_mov_b32_e32 v63, v0
	v_mov_b32_e32 v64, v0
	v_mov_b32_e32 v65, v0
	v_mov_b32_e32 v66, v0
	v_mov_b32_e32 v67, v0
	v_mov_b32_e32 v68, v0
	v_mov_b32_e32 v69, v0
	v_mov_b32_e32 v70, v0
	v_mov_b32_e32 v71, v0
	v_mov_b32_e32 v80, v0
	v_mov_b32_e32 v81, v0
	v_mov_b32_e32 v82, v0
	v_mov_b32_e32 v83, v0
	v_mov_b32_e32 v84, v0
	v_mov_b32_e32 v85, v0
	v_mov_b32_e32 v86, v0
	v_mov_b32_e32 v87, v0
	v_mov_b32_e32 v96, v0
	v_mov_b32_e32 v97, v0
	v_mov_b32_e32 v98, v0
	v_mov_b32_e32 v99, v0
	v_mov_b32_e32 v100, v0
	v_mov_b32_e32 v101, v0
	v_mov_b32_e32 v102, v0
	v_mov_b32_e32 v103, v0
	v_mov_b32_e32 v112, v0
	v_mov_b32_e32 v113, v0
	v_mov_b32_e32 v114, v0
	v_mov_b32_e32 v115, v0
	v_mov_b32_e32 v116, v0
	v_mov_b32_e32 v117, v0
	v_mov_b32_e32 v118, v0
	v_mov_b32_e32 v119, v0
	v_mov_b32_e32 v72, v0
	v_mov_b32_e32 v73, v0
	v_mov_b32_e32 v74, v0
	v_mov_b32_e32 v75, v0
	v_mov_b32_e32 v76, v0
	v_mov_b32_e32 v77, v0
	v_mov_b32_e32 v78, v0
	v_mov_b32_e32 v79, v0
	v_mov_b32_e32 v88, v0
	v_mov_b32_e32 v89, v0
	v_mov_b32_e32 v90, v0
	v_mov_b32_e32 v91, v0
	v_mov_b32_e32 v92, v0
	v_mov_b32_e32 v93, v0
	v_mov_b32_e32 v94, v0
	v_mov_b32_e32 v95, v0
	v_mov_b32_e32 v104, v0
	v_mov_b32_e32 v105, v0
	v_mov_b32_e32 v106, v0
	v_mov_b32_e32 v107, v0
	v_mov_b32_e32 v108, v0
	v_mov_b32_e32 v109, v0
	v_mov_b32_e32 v110, v0
	v_mov_b32_e32 v111, v0
	v_mov_b32_e32 v120, v0
	v_mov_b32_e32 v121, v0
	v_mov_b32_e32 v122, v0
	v_mov_b32_e32 v123, v0
	v_mov_b32_e32 v124, v0
	v_mov_b32_e32 v125, v0
	v_mov_b32_e32 v126, v0
	v_mov_b32_e32 v127, v0
	.p2align 6

.LBB0_577:
	v_exp_f32_e32 v219, v144
	v_exp_f32_e32 v225, v145
	v_exp_f32_e32 v227, v146
	v_exp_f32_e32 v248, v147
	ds_read_b128 v[144:147], v208 offset:36864
	v_exp_f32_e32 v240, v148
	v_exp_f32_e32 v242, v149
	v_exp_f32_e32 v244, v150
	v_exp_f32_e32 v246, v151
	v_cvt_pk_bf16_f32 v148, v219, v225
	v_cvt_pk_bf16_f32 v149, v227, v248
	v_cvt_pk_bf16_f32 v150, v240, v242
	v_cvt_pk_bf16_f32 v151, v244, v246
	ds_read_b128 v[228:231], v208 offset:36896
	ds_read_b128 v[232:235], v208 offset:41472
	s_waitcnt lgkmcnt(2)
	v_mfma_f32_32x32x16_bf16 v[64:79], v[144:147], v[148:151], v[64:79]
	v_add_f32_e32 v128, v129, v128
	v_add_f32_e32 v129, v161, v160
	ds_read_b128 v[144:147], v208 offset:46080
	ds_read_b128 v[236:239], v208 offset:41504
	v_add_f32_e32 v128, v130, v128
	v_add_f32_e32 v129, v162, v129
	v_add_f32_e32 v128, v131, v128
	v_add_f32_e32 v129, v163, v129
	s_waitcnt lgkmcnt(2)
	v_mfma_f32_32x32x16_bf16 v[48:63], v[232:235], v[148:151], v[48:63]
	v_add_f32_e32 v132, v132, v128
	v_add_f32_e32 v233, v164, v129
	ds_read_b128 v[128:131], v208 offset:50688
	ds_read_b128 v[160:163], v208 offset:46112
	v_exp_f32_e32 v152, v152
	v_exp_f32_e32 v164, v153
	v_exp_f32_e32 v154, v154
	v_exp_f32_e32 v232, v155
	s_waitcnt lgkmcnt(3)
	v_mfma_f32_32x32x16_bf16 v[32:47], v[144:147], v[148:151], v[32:47]
	v_exp_f32_e32 v156, v156
	ds_read_b128 v[144:147], v208 offset:50720
	v_add_f32_e32 v132, v133, v132
	v_add_f32_e32 v133, v165, v233
	v_add_f32_e32 v133, v166, v133
	v_exp_f32_e32 v166, v112
	v_add_f32_e32 v132, v134, v132
	s_waitcnt lgkmcnt(2)
	v_mfma_f32_32x32x16_bf16 v[0:15], v[128:131], v[148:151], v[0:15]
	v_exp_f32_e32 v148, v157
	v_exp_f32_e32 v150, v158
	v_exp_f32_e32 v158, v159
	v_cvt_pk_bf16_f32 v128, v152, v164
	v_cvt_pk_bf16_f32 v129, v154, v232
	v_cvt_pk_bf16_f32 v130, v156, v148
	v_cvt_pk_bf16_f32 v131, v150, v158
	v_add_f32_e32 v132, v135, v132
	v_add_f32_e32 v133, v167, v133
	s_waitcnt lgkmcnt(1)
	v_mfma_f32_32x32x16_bf16 v[32:47], v[160:163], v[128:131], v[32:47]
	v_exp_f32_e32 v160, v113
	v_exp_f32_e32 v161, v114
	v_exp_f32_e32 v162, v115
	ds_read_b128 v[112:115], v208 offset:36928
	v_add_f32_e32 v132, v136, v132
	v_add_f32_e32 v133, v168, v133
	v_exp_f32_e32 v241, v116
	v_mfma_f32_32x32x16_bf16 v[64:79], v[228:231], v[128:131], v[64:79]
	v_exp_f32_e32 v243, v117
	v_exp_f32_e32 v245, v118
	v_exp_f32_e32 v247, v119
	v_add_f32_e32 v132, v137, v132
	v_add_f32_e32 v133, v169, v133
	v_add_f32_e32 v132, v138, v132
	v_add_f32_e32 v133, v170, v133
	v_mfma_f32_32x32x16_bf16 v[48:63], v[236:239], v[128:131], v[48:63]
	v_add_f32_e32 v136, v139, v132
	v_add_f32_e32 v137, v171, v133
	v_cvt_pk_bf16_f32 v116, v166, v160
	v_cvt_pk_bf16_f32 v117, v161, v162
	v_cvt_pk_bf16_f32 v118, v241, v243
	v_cvt_pk_bf16_f32 v119, v245, v247
	v_exp_f32_e32 v153, v120
	s_waitcnt lgkmcnt(1)
	v_mfma_f32_32x32x16_bf16 v[0:15], v[144:147], v[128:131], v[0:15]
	ds_read_b128 v[128:131], v208 offset:41536
	ds_read_b128 v[132:135], v208 offset:36960
	v_exp_f32_e32 v165, v121
	v_add_f32_e32 v120, v225, v219
	v_add_f32_e32 v121, v160, v166
	v_add_f32_e32 v120, v227, v120
	s_waitcnt lgkmcnt(2)
	v_mfma_f32_32x32x16_bf16 v[64:79], v[112:115], v[116:119], v[64:79]
	v_add_f32_e32 v112, v140, v136
	v_add_f32_e32 v113, v172, v137
	v_add_f32_e32 v112, v141, v112
	v_add_f32_e32 v140, v173, v113
	v_add_f32_e32 v141, v142, v112
	ds_read_b128 v[112:115], v208 offset:46144
	ds_read_b128 v[136:139], v208 offset:41568
	v_add_f32_e32 v121, v161, v121
	s_waitcnt lgkmcnt(3)
	v_mfma_f32_32x32x16_bf16 v[48:63], v[128:131], v[116:119], v[48:63]
	v_add_f32_e32 v128, v174, v140
	v_add_f32_e32 v129, v143, v141
	v_add_f32_e32 v128, v175, v128
	v_add_f32_e32 v128, v129, v128
	v_add_f32_e32 v144, v218, v128
	ds_read_b128 v[128:131], v208 offset:50752
	ds_read_b128 v[140:143], v208 offset:46176
	v_add_f32_e32 v120, v248, v120
	s_waitcnt lgkmcnt(3)
	v_mfma_f32_32x32x16_bf16 v[32:47], v[112:115], v[116:119], v[32:47]
	ds_read_b128 v[112:115], v208 offset:50784
	v_add_f32_e32 v121, v162, v121
	v_add_f32_e64 v120, v240, v120
	v_add_f32_e64 v121, v241, v121
	v_exp_f32_e32 v155, v122
	v_exp_f32_e32 v233, v123
	v_exp_f32_e32 v157, v124
	v_exp_f32_e32 v149, v125
	s_waitcnt lgkmcnt(2)
	v_mfma_f32_32x32x16_bf16 v[0:15], v[128:131], v[116:119], v[0:15]
	v_exp_f32_e32 v151, v126
	v_exp_f32_e32 v159, v127
	v_add_f32_e32 v120, v242, v120
	v_add_f32_e32 v121, v243, v121
	v_cvt_pk_bf16_f32 v116, v153, v165
	v_add_f32_e32 v120, v244, v120
	v_add_f32_e32 v121, v245, v121
	v_cvt_pk_bf16_f32 v117, v155, v233
	v_add_f32_e32 v120, v246, v120
	v_add_f32_e32 v121, v247, v121
	v_cvt_pk_bf16_f32 v118, v157, v149
	v_add_f32_e32 v120, v152, v120
	v_add_f32_e32 v121, v153, v121
	v_cvt_pk_bf16_f32 v119, v151, v159
	v_add_f32_e32 v120, v164, v120
	v_add_f32_e32 v121, v165, v121
	s_add_i32 s53, s53, 2
	v_mfma_f32_32x32x16_bf16 v[64:79], v[132:135], v[116:119], v[64:79]
	v_add_f32_e64 v120, v154, v120
	v_add_f32_e64 v121, v155, v121
	s_addk_i32 s52, 0x2000
	v_add_f32_e64 v120, v232, v120
	v_add_f32_e64 v121, v233, v121
	s_andn2_b64 vcc, exec, s[16:17]
	v_add_f32_e32 v120, v156, v120
	v_add_f32_e32 v121, v157, v121
	s_addk_i32 s51, 0x80
	v_add_f32_e32 v120, v148, v120
	v_add_f32_e32 v121, v149, v121
	v_mfma_f32_32x32x16_bf16 v[48:63], v[136:139], v[116:119], v[48:63]
	v_add_f32_e64 v120, v150, v120
	v_add_f32_e64 v121, v151, v121
	v_add_f32_e64 v120, v158, v120
	v_add_f32_e64 v121, v159, v121
	v_add_f32_e32 v120, v120, v121
	v_add_f32_e32 v218, v144, v120
	s_waitcnt lgkmcnt(1)
	v_mfma_f32_32x32x16_bf16 v[32:47], v[140:143], v[116:119], v[32:47]
	s_waitcnt lgkmcnt(0)
	v_mfma_f32_32x32x16_bf16 v[0:15], v[112:115], v[116:119], v[0:15]
	s_cbranch_vccz .LBB0_594
	.p2align 6

.LBB0_596:
	v_exp_f32_e32 v227, v144
	v_exp_f32_e32 v248, v145
	v_exp_f32_e32 v249, v146
	v_exp_f32_e32 v250, v147
	ds_read_b128 v[144:147], v208 offset:36864
	v_exp_f32_e32 v240, v148
	v_exp_f32_e32 v242, v149
	v_exp_f32_e32 v244, v150
	v_exp_f32_e32 v246, v151
	v_cvt_pk_bf16_f32 v148, v227, v248
	v_cvt_pk_bf16_f32 v149, v249, v250
	v_cvt_pk_bf16_f32 v150, v240, v242
	v_cvt_pk_bf16_f32 v151, v244, v246
	ds_read_b128 v[228:231], v208 offset:36896
	ds_read_b128 v[232:235], v208 offset:41472
	s_waitcnt lgkmcnt(2)
	v_mfma_f32_32x32x16_bf16 v[0:15], v[144:147], v[148:151], v[0:15]
	v_add_f32_e32 v128, v129, v128
	v_add_f32_e32 v129, v161, v160
	ds_read_b128 v[144:147], v208 offset:46080
	ds_read_b128 v[236:239], v208 offset:41504
	v_add_f32_e32 v128, v130, v128
	v_add_f32_e32 v129, v162, v129
	v_add_f32_e32 v128, v131, v128
	v_add_f32_e32 v129, v163, v129
	s_waitcnt lgkmcnt(2)
	v_mfma_f32_32x32x16_bf16 v[48:63], v[232:235], v[148:151], v[48:63]
	v_add_f32_e32 v132, v132, v128
	v_add_f32_e32 v233, v164, v129
	ds_read_b128 v[128:131], v208 offset:50688
	ds_read_b128 v[160:163], v208 offset:46112
	v_exp_f32_e32 v152, v152
	v_exp_f32_e32 v164, v153
	v_exp_f32_e32 v154, v154
	v_exp_f32_e32 v232, v155
	s_waitcnt lgkmcnt(3)
	v_mfma_f32_32x32x16_bf16 v[32:47], v[144:147], v[148:151], v[32:47]
	v_exp_f32_e32 v156, v156
	ds_read_b128 v[144:147], v208 offset:50720
	v_add_f32_e32 v132, v133, v132
	v_add_f32_e32 v133, v165, v233
	v_add_f32_e32 v133, v166, v133
	v_exp_f32_e32 v166, v112
	v_add_f32_e32 v132, v134, v132
	s_waitcnt lgkmcnt(2)
	v_mfma_f32_32x32x16_bf16 v[16:31], v[128:131], v[148:151], v[16:31]
	v_exp_f32_e32 v148, v157
	v_exp_f32_e32 v150, v158
	v_exp_f32_e32 v158, v159
	v_cvt_pk_bf16_f32 v128, v152, v164
	v_cvt_pk_bf16_f32 v129, v154, v232
	v_cvt_pk_bf16_f32 v130, v156, v148
	v_cvt_pk_bf16_f32 v131, v150, v158
	v_add_f32_e32 v132, v135, v132
	v_add_f32_e32 v133, v167, v133
	s_waitcnt lgkmcnt(1)
	v_mfma_f32_32x32x16_bf16 v[32:47], v[160:163], v[128:131], v[32:47]
	v_exp_f32_e32 v160, v113
	v_exp_f32_e32 v161, v114
	v_exp_f32_e32 v162, v115
	ds_read_b128 v[112:115], v208 offset:36928
	v_add_f32_e32 v132, v136, v132
	v_add_f32_e32 v133, v168, v133
	v_exp_f32_e32 v241, v116
	v_mfma_f32_32x32x16_bf16 v[0:15], v[228:231], v[128:131], v[0:15]
	v_exp_f32_e32 v243, v117
	v_exp_f32_e32 v245, v118
	v_exp_f32_e32 v247, v119
	v_add_f32_e32 v132, v137, v132
	v_add_f32_e32 v133, v169, v133
	v_add_f32_e32 v132, v138, v132
	v_add_f32_e32 v133, v170, v133
	v_mfma_f32_32x32x16_bf16 v[48:63], v[236:239], v[128:131], v[48:63]
	v_add_f32_e32 v136, v139, v132
	v_add_f32_e32 v137, v171, v133
	v_cvt_pk_bf16_f32 v116, v166, v160
	v_cvt_pk_bf16_f32 v117, v161, v162
	v_cvt_pk_bf16_f32 v118, v241, v243
	v_cvt_pk_bf16_f32 v119, v245, v247
	v_exp_f32_e32 v153, v120
	s_waitcnt lgkmcnt(1)
	v_mfma_f32_32x32x16_bf16 v[16:31], v[144:147], v[128:131], v[16:31]
	ds_read_b128 v[128:131], v208 offset:41536
	ds_read_b128 v[132:135], v208 offset:36960
	v_exp_f32_e32 v165, v121
	v_add_f32_e32 v120, v248, v227
	v_add_f32_e32 v121, v160, v166
	v_add_f32_e32 v120, v249, v120
	s_waitcnt lgkmcnt(2)
	v_mfma_f32_32x32x16_bf16 v[0:15], v[112:115], v[116:119], v[0:15]
	v_add_f32_e32 v112, v140, v136
	v_add_f32_e32 v113, v172, v137
	v_add_f32_e32 v112, v141, v112
	v_add_f32_e32 v140, v173, v113
	v_add_f32_e32 v141, v142, v112
	ds_read_b128 v[112:115], v208 offset:46144
	ds_read_b128 v[136:139], v208 offset:41568
	v_add_f32_e32 v121, v161, v121
	s_waitcnt lgkmcnt(3)
	v_mfma_f32_32x32x16_bf16 v[48:63], v[128:131], v[116:119], v[48:63]
	v_add_f32_e32 v128, v174, v140
	v_add_f32_e32 v129, v143, v141
	v_add_f32_e32 v128, v175, v128
	v_add_f32_e32 v128, v129, v128
	v_add_f32_e32 v144, v213, v128
	ds_read_b128 v[128:131], v208 offset:50752
	ds_read_b128 v[140:143], v208 offset:46176
	v_add_f32_e32 v120, v250, v120
	s_waitcnt lgkmcnt(3)
	v_mfma_f32_32x32x16_bf16 v[32:47], v[112:115], v[116:119], v[32:47]
	ds_read_b128 v[112:115], v208 offset:50784
	v_add_f32_e32 v121, v162, v121
	v_add_f32_e64 v120, v240, v120
	v_add_f32_e64 v121, v241, v121
	v_exp_f32_e32 v155, v122
	v_exp_f32_e32 v233, v123
	v_exp_f32_e32 v157, v124
	v_exp_f32_e32 v149, v125
	s_waitcnt lgkmcnt(2)
	v_mfma_f32_32x32x16_bf16 v[16:31], v[128:131], v[116:119], v[16:31]
	v_exp_f32_e32 v151, v126
	v_exp_f32_e32 v159, v127
	v_add_f32_e32 v120, v242, v120
	v_add_f32_e32 v121, v243, v121
	v_cvt_pk_bf16_f32 v116, v153, v165
	v_add_f32_e32 v120, v244, v120
	v_add_f32_e32 v121, v245, v121
	v_cvt_pk_bf16_f32 v117, v155, v233
	v_add_f32_e32 v120, v246, v120
	v_add_f32_e32 v121, v247, v121
	v_cvt_pk_bf16_f32 v118, v157, v149
	v_add_f32_e32 v120, v152, v120
	v_add_f32_e32 v121, v153, v121
	v_cvt_pk_bf16_f32 v119, v151, v159
	v_add_f32_e32 v120, v164, v120
	v_add_f32_e32 v121, v165, v121
	s_add_i32 s18, s18, 2
	v_mfma_f32_32x32x16_bf16 v[0:15], v[132:135], v[116:119], v[0:15]
	v_add_f32_e64 v120, v154, v120
	v_add_f32_e64 v121, v155, v121
	s_addk_i32 s37, 0x2000
	v_add_f32_e64 v120, v232, v120
	v_add_f32_e64 v121, v233, v121
	s_andn2_b64 vcc, exec, s[12:13]
	v_add_f32_e32 v120, v156, v120
	v_add_f32_e32 v121, v157, v121
	s_addk_i32 s19, 0x80
	v_add_f32_e32 v120, v148, v120
	v_add_f32_e32 v121, v149, v121
	v_mfma_f32_32x32x16_bf16 v[48:63], v[136:139], v[116:119], v[48:63]
	v_add_f32_e64 v120, v150, v120
	v_add_f32_e64 v121, v151, v121
	v_add_f32_e64 v120, v158, v120
	v_add_f32_e64 v121, v159, v121
	v_add_f32_e32 v120, v120, v121
	v_add_f32_e32 v213, v144, v120
	s_waitcnt lgkmcnt(1)
	v_mfma_f32_32x32x16_bf16 v[32:47], v[140:143], v[116:119], v[32:47]
	s_waitcnt lgkmcnt(0)
	v_mfma_f32_32x32x16_bf16 v[16:31], v[112:115], v[116:119], v[16:31]
	s_cbranch_vccz .LBB0_574
	.p2align 6

; template <class Epi, class Sched, bool ALIGN_EPI = false, bool SP2 = false, bool F16 = false, bool TOKPERM = false>
; __device__ __forceinline__ void gemm_phase(PG8_LAS unsigned char* lds, const Gemm g, const Sched& S, const Epi& E, int wv) {
;     ...
;         const bool has_next = S.next(ui + 1, nxt);
;         const char* nA = has_next ? (const char*)g.A + (size_t)nxt.pm * tstep : cA; const char* nB = has_next ? (const char*)g.Bt + (size_t)nxt.pn * tstep : cB;
;     ...
; #pragma unroll
;         for (int a = 0; a < 2; ++a)
; #pragma unroll
;             for (int b = 0; b < 2; ++b)
; #pragma unroll
;                 for (int m = 0; m < 4; ++m)
; #pragma unroll
;                     for (int n = 0; n < 2; ++n) acc[a][b][m][n] = (f32x4){0.f, 0.f, 0.f, 0.f};
.LBB0_684:
	s_ashr_i32 s13, s12, 31
	v_cmp_lt_i64_e32 vcc, s[16:17], v[142:143]
	s_lshl_b64 s[16:17], s[12:13], 19
	s_add_u32 s16, s30, s16
	s_addc_u32 s17, s31, s17
	s_and_b64 s[18:19], vcc, exec
	s_cselect_b32 s13, s17, s53
	s_cselect_b32 s49, s16, s52
	s_ashr_i32 s11, s10, 31
	s_lshl_b64 s[18:19], s[10:11], 19
	s_add_u32 s18, s14, s18
	s_addc_u32 s19, s15, s19
	s_and_b64 s[56:57], vcc, exec
	s_cselect_b32 s11, s19, s55
	s_cselect_b32 s66, s18, s54
	s_add_u32 s52, s52, 0x40080
	s_addc_u32 s53, s53, 0
	s_add_u32 s67, s54, 0x100
	v_mov_b32_e32 v0, 0
	s_addc_u32 s68, s55, 0
	s_mov_b32 s69, -2
	s_waitcnt lgkmcnt(0)
	v_mov_b32_e32 v1, v0
	v_mov_b32_e32 v2, v0
	v_mov_b32_e32 v3, v0
	v_mov_b32_e32 v4, v0
	v_mov_b32_e32 v5, v0
	v_mov_b32_e32 v6, v0
	v_mov_b32_e32 v7, v0
	v_mov_b32_e32 v16, v0
	v_mov_b32_e32 v17, v0
	v_mov_b32_e32 v18, v0
	v_mov_b32_e32 v19, v0
	v_mov_b32_e32 v20, v0
	v_mov_b32_e32 v21, v0
	v_mov_b32_e32 v22, v0
	v_mov_b32_e32 v23, v0
	v_mov_b32_e32 v32, v0
	v_mov_b32_e32 v33, v0
	v_mov_b32_e32 v34, v0
	v_mov_b32_e32 v35, v0
	v_mov_b32_e32 v36, v0
	v_mov_b32_e32 v37, v0
	v_mov_b32_e32 v38, v0
	v_mov_b32_e32 v39, v0
	v_mov_b32_e32 v48, v0
	v_mov_b32_e32 v49, v0
	v_mov_b32_e32 v50, v0
	v_mov_b32_e32 v51, v0
	v_mov_b32_e32 v52, v0
	v_mov_b32_e32 v53, v0
	v_mov_b32_e32 v54, v0
	v_mov_b32_e32 v55, v0
	v_mov_b32_e32 v8, v0
	v_mov_b32_e32 v9, v0
	v_mov_b32_e32 v10, v0
	v_mov_b32_e32 v11, v0
	v_mov_b32_e32 v12, v0
	v_mov_b32_e32 v13, v0
	v_mov_b32_e32 v14, v0
	v_mov_b32_e32 v15, v0
	v_mov_b32_e32 v24, v0
	v_mov_b32_e32 v25, v0
	v_mov_b32_e32 v26, v0
	v_mov_b32_e32 v27, v0
	v_mov_b32_e32 v28, v0
	v_mov_b32_e32 v29, v0
	v_mov_b32_e32 v30, v0
	v_mov_b32_e32 v31, v0
	v_mov_b32_e32 v40, v0
	v_mov_b32_e32 v41, v0
	v_mov_b32_e32 v42, v0
	v_mov_b32_e32 v43, v0
	v_mov_b32_e32 v44, v0
	v_mov_b32_e32 v45, v0
	v_mov_b32_e32 v46, v0
	v_mov_b32_e32 v47, v0
	v_mov_b32_e32 v56, v0
	v_mov_b32_e32 v57, v0
	v_mov_b32_e32 v58, v0
	v_mov_b32_e32 v59, v0
	v_mov_b32_e32 v60, v0
	v_mov_b32_e32 v61, v0
	v_mov_b32_e32 v62, v0
	v_mov_b32_e32 v63, v0
	v_mov_b32_e32 v64, v0
	v_mov_b32_e32 v65, v0
	v_mov_b32_e32 v66, v0
	v_mov_b32_e32 v67, v0
	v_mov_b32_e32 v68, v0
	v_mov_b32_e32 v69, v0
	v_mov_b32_e32 v70, v0
	v_mov_b32_e32 v71, v0
	v_mov_b32_e32 v80, v0
	v_mov_b32_e32 v81, v0
	v_mov_b32_e32 v82, v0
	v_mov_b32_e32 v83, v0
	v_mov_b32_e32 v84, v0
	v_mov_b32_e32 v85, v0
	v_mov_b32_e32 v86, v0
	v_mov_b32_e32 v87, v0
	v_mov_b32_e32 v96, v0
	v_mov_b32_e32 v97, v0
	v_mov_b32_e32 v98, v0
	v_mov_b32_e32 v99, v0
	v_mov_b32_e32 v100, v0
	v_mov_b32_e32 v101, v0
	v_mov_b32_e32 v102, v0
	v_mov_b32_e32 v103, v0
	v_mov_b32_e32 v112, v0
	v_mov_b32_e32 v113, v0
	v_mov_b32_e32 v114, v0
	v_mov_b32_e32 v115, v0
	v_mov_b32_e32 v116, v0
	v_mov_b32_e32 v117, v0
	v_mov_b32_e32 v118, v0
	v_mov_b32_e32 v119, v0
	v_mov_b32_e32 v72, v0
	v_mov_b32_e32 v73, v0
	v_mov_b32_e32 v74, v0
	v_mov_b32_e32 v75, v0
	v_mov_b32_e32 v76, v0
	v_mov_b32_e32 v77, v0
	v_mov_b32_e32 v78, v0
	v_mov_b32_e32 v79, v0
	v_mov_b32_e32 v88, v0
	v_mov_b32_e32 v89, v0
	v_mov_b32_e32 v90, v0
	v_mov_b32_e32 v91, v0
	v_mov_b32_e32 v92, v0
	v_mov_b32_e32 v93, v0
	v_mov_b32_e32 v94, v0
	v_mov_b32_e32 v95, v0
	v_mov_b32_e32 v104, v0
	v_mov_b32_e32 v105, v0
	v_mov_b32_e32 v106, v0
	v_mov_b32_e32 v107, v0
	v_mov_b32_e32 v108, v0
	v_mov_b32_e32 v109, v0
	v_mov_b32_e32 v110, v0
	v_mov_b32_e32 v111, v0
	v_mov_b32_e32 v120, v0
	v_mov_b32_e32 v121, v0
	v_mov_b32_e32 v122, v0
	v_mov_b32_e32 v123, v0
	v_mov_b32_e32 v124, v0
	v_mov_b32_e32 v125, v0
	v_mov_b32_e32 v126, v0
	v_mov_b32_e32 v127, v0
	.p2align 6

; template <class Epi, class Sched, bool ALIGN_EPI = false, bool SP2 = false, bool F16 = false, bool TOKPERM = false>
; __device__ __forceinline__ void gemm_phase(PG8_LAS unsigned char* lds, const Gemm g, const Sched& S, const Epi& E, int wv) {
;     ...
;         const bool has_next = S.next(ui + 1, nxt);
;         const char* nA = has_next ? (const char*)g.A + (size_t)nxt.pm * tstep : cA; const char* nB = has_next ? (const char*)g.Bt + (size_t)nxt.pn * tstep : cB;
;     ...
; #pragma unroll
;         for (int a = 0; a < 2; ++a)
; #pragma unroll
;             for (int b = 0; b < 2; ++b)
; #pragma unroll
;                 for (int m = 0; m < 4; ++m)
; #pragma unroll
;                     for (int n = 0; n < 2; ++n) acc[a][b][m][n] = (f32x4){0.f, 0.f, 0.f, 0.f};
.LBB0_767:
	s_ashr_i32 s53, s52, 31
	s_lshl_b64 s[54:55], s[52:53], 19
	s_add_u32 s54, s40, s54
	s_addc_u32 s55, s41, s55
	s_and_b64 s[56:57], s[6:7], exec
	s_cselect_b32 s53, s55, s11
	s_cselect_b32 s70, s54, s10
	s_ashr_i32 s51, s50, 31
	s_lshl_b64 s[56:57], s[50:51], 19
	s_add_u32 s56, s0, s56
	s_addc_u32 s57, s1, s57
	s_and_b64 s[58:59], s[6:7], exec
	s_cselect_b32 s51, s57, s13
	s_cselect_b32 s71, s56, s12
	s_add_u32 s10, s10, 0x40080
	s_addc_u32 s11, s11, 0
	s_add_u32 s72, s12, 0x100
	v_mov_b32_e32 v0, 0
	s_addc_u32 s73, s13, 0
	s_mov_b32 s74, -2
	v_mov_b32_e32 v1, v0
	v_mov_b32_e32 v2, v0
	v_mov_b32_e32 v3, v0
	v_mov_b32_e32 v4, v0
	v_mov_b32_e32 v5, v0
	v_mov_b32_e32 v6, v0
	v_mov_b32_e32 v7, v0
	v_mov_b32_e32 v16, v0
	v_mov_b32_e32 v17, v0
	v_mov_b32_e32 v18, v0
	v_mov_b32_e32 v19, v0
	v_mov_b32_e32 v20, v0
	v_mov_b32_e32 v21, v0
	v_mov_b32_e32 v22, v0
	v_mov_b32_e32 v23, v0
	v_mov_b32_e32 v32, v0
	v_mov_b32_e32 v33, v0
	v_mov_b32_e32 v34, v0
	v_mov_b32_e32 v35, v0
	v_mov_b32_e32 v36, v0
	v_mov_b32_e32 v37, v0
	v_mov_b32_e32 v38, v0
	v_mov_b32_e32 v39, v0
	v_mov_b32_e32 v48, v0
	v_mov_b32_e32 v49, v0
	v_mov_b32_e32 v50, v0
	v_mov_b32_e32 v51, v0
	v_mov_b32_e32 v52, v0
	v_mov_b32_e32 v53, v0
	v_mov_b32_e32 v54, v0
	v_mov_b32_e32 v55, v0
	v_mov_b32_e32 v8, v0
	v_mov_b32_e32 v9, v0
	v_mov_b32_e32 v10, v0
	v_mov_b32_e32 v11, v0
	v_mov_b32_e32 v12, v0
	v_mov_b32_e32 v13, v0
	v_mov_b32_e32 v14, v0
	v_mov_b32_e32 v15, v0
	v_mov_b32_e32 v24, v0
	v_mov_b32_e32 v25, v0
	v_mov_b32_e32 v26, v0
	v_mov_b32_e32 v27, v0
	v_mov_b32_e32 v28, v0
	v_mov_b32_e32 v29, v0
	v_mov_b32_e32 v30, v0
	v_mov_b32_e32 v31, v0
	v_mov_b32_e32 v40, v0
	v_mov_b32_e32 v41, v0
	v_mov_b32_e32 v42, v0
	v_mov_b32_e32 v43, v0
	v_mov_b32_e32 v44, v0
	v_mov_b32_e32 v45, v0
	v_mov_b32_e32 v46, v0
	v_mov_b32_e32 v47, v0
	v_mov_b32_e32 v56, v0
	v_mov_b32_e32 v57, v0
	v_mov_b32_e32 v58, v0
	v_mov_b32_e32 v59, v0
	v_mov_b32_e32 v60, v0
	v_mov_b32_e32 v61, v0
	v_mov_b32_e32 v62, v0
	v_mov_b32_e32 v63, v0
	v_mov_b32_e32 v64, v0
	v_mov_b32_e32 v65, v0
	v_mov_b32_e32 v66, v0
	v_mov_b32_e32 v67, v0
	v_mov_b32_e32 v68, v0
	v_mov_b32_e32 v69, v0
	v_mov_b32_e32 v70, v0
	v_mov_b32_e32 v71, v0
	v_mov_b32_e32 v80, v0
	v_mov_b32_e32 v81, v0
	v_mov_b32_e32 v82, v0
	v_mov_b32_e32 v83, v0
	v_mov_b32_e32 v84, v0
	v_mov_b32_e32 v85, v0
	v_mov_b32_e32 v86, v0
	v_mov_b32_e32 v87, v0
	v_mov_b32_e32 v96, v0
	v_mov_b32_e32 v97, v0
	v_mov_b32_e32 v98, v0
	v_mov_b32_e32 v99, v0
	v_mov_b32_e32 v100, v0
	v_mov_b32_e32 v101, v0
	v_mov_b32_e32 v102, v0
	v_mov_b32_e32 v103, v0
	v_mov_b32_e32 v112, v0
	v_mov_b32_e32 v113, v0
	v_mov_b32_e32 v114, v0
	v_mov_b32_e32 v115, v0
	v_mov_b32_e32 v120, v0
	v_mov_b32_e32 v121, v0
	v_mov_b32_e32 v122, v0
	v_mov_b32_e32 v123, v0
	v_mov_b32_e32 v72, v0
	v_mov_b32_e32 v73, v0
	v_mov_b32_e32 v74, v0
	v_mov_b32_e32 v75, v0
	v_mov_b32_e32 v76, v0
	v_mov_b32_e32 v77, v0
	v_mov_b32_e32 v78, v0
	v_mov_b32_e32 v79, v0
	v_mov_b32_e32 v88, v0
	v_mov_b32_e32 v89, v0
	v_mov_b32_e32 v90, v0
	v_mov_b32_e32 v91, v0
	v_mov_b32_e32 v92, v0
	v_mov_b32_e32 v93, v0
	v_mov_b32_e32 v94, v0
	v_mov_b32_e32 v95, v0
	v_mov_b32_e32 v104, v0
	v_mov_b32_e32 v105, v0
	v_mov_b32_e32 v106, v0
	v_mov_b32_e32 v107, v0
	v_mov_b32_e32 v108, v0
	v_mov_b32_e32 v109, v0
	v_mov_b32_e32 v110, v0
	v_mov_b32_e32 v111, v0
	v_mov_b32_e32 v116, v0
	v_mov_b32_e32 v117, v0
	v_mov_b32_e32 v118, v0
	v_mov_b32_e32 v119, v0
	v_mov_b32_e32 v124, v0
	v_mov_b32_e32 v125, v0
	v_mov_b32_e32 v126, v0
	v_mov_b32_e32 v127, v0
	.p2align 6

; template <class Epi, class Sched, bool ALIGN_EPI = false, bool SP2 = false, bool F16 = false, bool TOKPERM = false>
; __device__ __forceinline__ void gemm_phase(PG8_LAS unsigned char* lds, const Gemm g, const Sched& S, const Epi& E, int wv) {
;     ...
; #pragma unroll
;         for (int a = 0; a < 2; ++a)
; #pragma unroll
;             for (int b = 0; b < 2; ++b)
; #pragma unroll
;                 for (int m = 0; m < 4; ++m)
; #pragma unroll
;                     for (int n = 0; n < 2; ++n) acc[a][b][m][n] = (f32x4){0.f, 0.f, 0.f, 0.f};
.LBB0_866:
	s_add_u32 s65, s18, 0x100
	v_mov_b32_e32 v0, 0
	s_addc_u32 s66, s19, 0
	s_mov_b32 s67, -2
	s_waitcnt lgkmcnt(0)
	v_mov_b32_e32 v1, v0
	v_mov_b32_e32 v2, v0
	v_mov_b32_e32 v3, v0
	v_mov_b32_e32 v4, v0
	v_mov_b32_e32 v5, v0
	v_mov_b32_e32 v6, v0
	v_mov_b32_e32 v7, v0
	v_mov_b32_e32 v16, v0
	v_mov_b32_e32 v17, v0
	v_mov_b32_e32 v18, v0
	v_mov_b32_e32 v19, v0
	v_mov_b32_e32 v20, v0
	v_mov_b32_e32 v21, v0
	v_mov_b32_e32 v22, v0
	v_mov_b32_e32 v23, v0
	v_mov_b32_e32 v32, v0
	v_mov_b32_e32 v33, v0
	v_mov_b32_e32 v34, v0
	v_mov_b32_e32 v35, v0
	v_mov_b32_e32 v36, v0
	v_mov_b32_e32 v37, v0
	v_mov_b32_e32 v38, v0
	v_mov_b32_e32 v39, v0
	v_mov_b32_e32 v48, v0
	v_mov_b32_e32 v49, v0
	v_mov_b32_e32 v50, v0
	v_mov_b32_e32 v51, v0
	v_mov_b32_e32 v52, v0
	v_mov_b32_e32 v53, v0
	v_mov_b32_e32 v54, v0
	v_mov_b32_e32 v55, v0
	v_mov_b32_e32 v8, v0
	v_mov_b32_e32 v9, v0
	v_mov_b32_e32 v10, v0
	v_mov_b32_e32 v11, v0
	v_mov_b32_e32 v12, v0
	v_mov_b32_e32 v13, v0
	v_mov_b32_e32 v14, v0
	v_mov_b32_e32 v15, v0
	v_mov_b32_e32 v24, v0
	v_mov_b32_e32 v25, v0
	v_mov_b32_e32 v26, v0
	v_mov_b32_e32 v27, v0
	v_mov_b32_e32 v28, v0
	v_mov_b32_e32 v29, v0
	v_mov_b32_e32 v30, v0
	v_mov_b32_e32 v31, v0
	v_mov_b32_e32 v40, v0
	v_mov_b32_e32 v41, v0
	v_mov_b32_e32 v42, v0
	v_mov_b32_e32 v43, v0
	v_mov_b32_e32 v44, v0
	v_mov_b32_e32 v45, v0
	v_mov_b32_e32 v46, v0
	v_mov_b32_e32 v47, v0
	v_mov_b32_e32 v56, v0
	v_mov_b32_e32 v57, v0
	v_mov_b32_e32 v58, v0
	v_mov_b32_e32 v59, v0
	v_mov_b32_e32 v60, v0
	v_mov_b32_e32 v61, v0
	v_mov_b32_e32 v62, v0
	v_mov_b32_e32 v63, v0
	v_mov_b32_e32 v64, v0
	v_mov_b32_e32 v65, v0
	v_mov_b32_e32 v66, v0
	v_mov_b32_e32 v67, v0
	v_mov_b32_e32 v68, v0
	v_mov_b32_e32 v69, v0
	v_mov_b32_e32 v70, v0
	v_mov_b32_e32 v71, v0
	v_mov_b32_e32 v80, v0
	v_mov_b32_e32 v81, v0
	v_mov_b32_e32 v82, v0
	v_mov_b32_e32 v83, v0
	v_mov_b32_e32 v84, v0
	v_mov_b32_e32 v85, v0
	v_mov_b32_e32 v86, v0
	v_mov_b32_e32 v87, v0
	v_mov_b32_e32 v96, v0
	v_mov_b32_e32 v97, v0
	v_mov_b32_e32 v98, v0
	v_mov_b32_e32 v99, v0
	v_mov_b32_e32 v100, v0
	v_mov_b32_e32 v101, v0
	v_mov_b32_e32 v102, v0
	v_mov_b32_e32 v103, v0
	v_mov_b32_e32 v112, v0
	v_mov_b32_e32 v113, v0
	v_mov_b32_e32 v114, v0
	v_mov_b32_e32 v115, v0
	v_mov_b32_e32 v116, v0
	v_mov_b32_e32 v117, v0
	v_mov_b32_e32 v118, v0
	v_mov_b32_e32 v119, v0
	v_mov_b32_e32 v72, v0
	v_mov_b32_e32 v73, v0
	v_mov_b32_e32 v74, v0
	v_mov_b32_e32 v75, v0
	v_mov_b32_e32 v76, v0
	v_mov_b32_e32 v77, v0
	v_mov_b32_e32 v78, v0
	v_mov_b32_e32 v79, v0
	v_mov_b32_e32 v88, v0
	v_mov_b32_e32 v89, v0
	v_mov_b32_e32 v90, v0
	v_mov_b32_e32 v91, v0
	v_mov_b32_e32 v92, v0
	v_mov_b32_e32 v93, v0
	v_mov_b32_e32 v94, v0
	v_mov_b32_e32 v95, v0
	v_mov_b32_e32 v104, v0
	v_mov_b32_e32 v105, v0
	v_mov_b32_e32 v106, v0
	v_mov_b32_e32 v107, v0
	v_mov_b32_e32 v108, v0
	v_mov_b32_e32 v109, v0
	v_mov_b32_e32 v110, v0
	v_mov_b32_e32 v111, v0
	v_mov_b32_e32 v120, v0
	v_mov_b32_e32 v121, v0
	v_mov_b32_e32 v122, v0
	v_mov_b32_e32 v123, v0
	v_mov_b32_e32 v124, v0
	v_mov_b32_e32 v125, v0
	v_mov_b32_e32 v126, v0
	v_mov_b32_e32 v127, v0
	.p2align 6

; template <class Epi, class Sched, bool ALIGN_EPI = false, bool SP2 = false, bool F16 = false, bool TOKPERM = false>
; __device__ __forceinline__ void gemm_phase(PG8_LAS unsigned char* lds, const Gemm g, const Sched& S, const Epi& E, int wv) {
;     ...
;         const bool has_next = S.next(ui + 1, nxt);
;         const char* nA = has_next ? (const char*)g.A + (size_t)nxt.pm * tstep : cA; const char* nB = has_next ? (const char*)g.Bt + (size_t)nxt.pn * tstep : cB;
;     ...
; #pragma unroll
;         for (int a = 0; a < 2; ++a)
; #pragma unroll
;             for (int b = 0; b < 2; ++b)
; #pragma unroll
;                 for (int m = 0; m < 4; ++m)
; #pragma unroll
;                     for (int n = 0; n < 2; ++n) acc[a][b][m][n] = (f32x4){0.f, 0.f, 0.f, 0.f};
;         cur = nxt; cA = nA; cB = nB; ++ui;
.LBB0_949:
	s_ashr_i32 s51, s50, 31
	s_lshl_b64 s[52:53], s[50:51], 19
	s_add_u32 s52, s40, s52
	s_addc_u32 s53, s41, s53
	s_and_b64 s[54:55], s[6:7], exec
	s_cselect_b32 s51, s53, s11
	s_cselect_b32 s70, s52, s10
	s_ashr_i32 s49, s48, 31
	s_lshl_b64 s[54:55], s[48:49], 19
	s_add_u32 s54, s0, s54
	s_addc_u32 s55, s1, s55
	s_and_b64 s[56:57], s[6:7], exec
	s_cselect_b32 s49, s55, s13
	s_cselect_b32 s71, s54, s12
	s_add_u32 s10, s10, 0x40080
	s_addc_u32 s11, s11, 0
	s_add_u32 s72, s12, 0x100
	v_mov_b32_e32 v0, 0
	s_addc_u32 s73, s13, 0
	s_mov_b32 s74, -2
	v_mov_b32_e32 v1, v0
	v_mov_b32_e32 v2, v0
	v_mov_b32_e32 v3, v0
	v_mov_b32_e32 v4, v0
	v_mov_b32_e32 v5, v0
	v_mov_b32_e32 v6, v0
	v_mov_b32_e32 v7, v0
	v_mov_b32_e32 v16, v0
	v_mov_b32_e32 v17, v0
	v_mov_b32_e32 v18, v0
	v_mov_b32_e32 v19, v0
	v_mov_b32_e32 v20, v0
	v_mov_b32_e32 v21, v0
	v_mov_b32_e32 v22, v0
	v_mov_b32_e32 v23, v0
	v_mov_b32_e32 v32, v0
	v_mov_b32_e32 v33, v0
	v_mov_b32_e32 v34, v0
	v_mov_b32_e32 v35, v0
	v_mov_b32_e32 v36, v0
	v_mov_b32_e32 v37, v0
	v_mov_b32_e32 v38, v0
	v_mov_b32_e32 v39, v0
	v_mov_b32_e32 v48, v0
	v_mov_b32_e32 v49, v0
	v_mov_b32_e32 v50, v0
	v_mov_b32_e32 v51, v0
	v_mov_b32_e32 v52, v0
	v_mov_b32_e32 v53, v0
	v_mov_b32_e32 v54, v0
	v_mov_b32_e32 v55, v0
	v_mov_b32_e32 v8, v0
	v_mov_b32_e32 v9, v0
	v_mov_b32_e32 v10, v0
	v_mov_b32_e32 v11, v0
	v_mov_b32_e32 v12, v0
	v_mov_b32_e32 v13, v0
	v_mov_b32_e32 v14, v0
	v_mov_b32_e32 v15, v0
	v_mov_b32_e32 v24, v0
	v_mov_b32_e32 v25, v0
	v_mov_b32_e32 v26, v0
	v_mov_b32_e32 v27, v0
	v_mov_b32_e32 v28, v0
	v_mov_b32_e32 v29, v0
	v_mov_b32_e32 v30, v0
	v_mov_b32_e32 v31, v0
	v_mov_b32_e32 v40, v0
	v_mov_b32_e32 v41, v0
	v_mov_b32_e32 v42, v0
	v_mov_b32_e32 v43, v0
	v_mov_b32_e32 v44, v0
	v_mov_b32_e32 v45, v0
	v_mov_b32_e32 v46, v0
	v_mov_b32_e32 v47, v0
	v_mov_b32_e32 v56, v0
	v_mov_b32_e32 v57, v0
	v_mov_b32_e32 v58, v0
	v_mov_b32_e32 v59, v0
	v_mov_b32_e32 v60, v0
	v_mov_b32_e32 v61, v0
	v_mov_b32_e32 v62, v0
	v_mov_b32_e32 v63, v0
	v_mov_b32_e32 v64, v0
	v_mov_b32_e32 v65, v0
	v_mov_b32_e32 v66, v0
	v_mov_b32_e32 v67, v0
	v_mov_b32_e32 v68, v0
	v_mov_b32_e32 v69, v0
	v_mov_b32_e32 v70, v0
	v_mov_b32_e32 v71, v0
	v_mov_b32_e32 v80, v0
	v_mov_b32_e32 v81, v0
	v_mov_b32_e32 v82, v0
	v_mov_b32_e32 v83, v0
	v_mov_b32_e32 v84, v0
	v_mov_b32_e32 v85, v0
	v_mov_b32_e32 v86, v0
	v_mov_b32_e32 v87, v0
	v_mov_b32_e32 v96, v0
	v_mov_b32_e32 v97, v0
	v_mov_b32_e32 v98, v0
	v_mov_b32_e32 v99, v0
	v_mov_b32_e32 v100, v0
	v_mov_b32_e32 v101, v0
	v_mov_b32_e32 v102, v0
	v_mov_b32_e32 v103, v0
	v_mov_b32_e32 v112, v0
	v_mov_b32_e32 v113, v0
	v_mov_b32_e32 v114, v0
	v_mov_b32_e32 v115, v0
	v_mov_b32_e32 v120, v0
	v_mov_b32_e32 v121, v0
	v_mov_b32_e32 v122, v0
	v_mov_b32_e32 v123, v0
	v_mov_b32_e32 v72, v0
	v_mov_b32_e32 v73, v0
	v_mov_b32_e32 v74, v0
	v_mov_b32_e32 v75, v0
	v_mov_b32_e32 v76, v0
	v_mov_b32_e32 v77, v0
	v_mov_b32_e32 v78, v0
	v_mov_b32_e32 v79, v0
	v_mov_b32_e32 v88, v0
	v_mov_b32_e32 v89, v0
	v_mov_b32_e32 v90, v0
	v_mov_b32_e32 v91, v0
	v_mov_b32_e32 v92, v0
	v_mov_b32_e32 v93, v0
	v_mov_b32_e32 v94, v0
	v_mov_b32_e32 v95, v0
	v_mov_b32_e32 v104, v0
	v_mov_b32_e32 v105, v0
	v_mov_b32_e32 v106, v0
	v_mov_b32_e32 v107, v0
	v_mov_b32_e32 v108, v0
	v_mov_b32_e32 v109, v0
	v_mov_b32_e32 v110, v0
	v_mov_b32_e32 v111, v0
	v_mov_b32_e32 v116, v0
	v_mov_b32_e32 v117, v0
	v_mov_b32_e32 v118, v0
	v_mov_b32_e32 v119, v0
	v_mov_b32_e32 v124, v0
	v_mov_b32_e32 v125, v0
	v_mov_b32_e32 v126, v0
	v_mov_b32_e32 v127, v0
	.p2align 6

; template <class Epi, class Sched, bool ALIGN_EPI = false, bool SP2 = false, bool F16 = false, bool TOKPERM = false>
; __device__ __forceinline__ void gemm_phase(PG8_LAS unsigned char* lds, const Gemm g, const Sched& S, const Epi& E, int wv) {
;     ...
;         const bool has_next = S.next(ui + 1, nxt);
;         const char* nA = has_next ? (const char*)g.A + (size_t)nxt.pm * tstep : cA; const char* nB = has_next ? (const char*)g.Bt + (size_t)nxt.pn * tstep : cB;
;     ...
; #pragma unroll
;         for (int a = 0; a < 2; ++a)
; #pragma unroll
;             for (int b = 0; b < 2; ++b)
; #pragma unroll
;                 for (int m = 0; m < 4; ++m)
; #pragma unroll
;                     for (int n = 0; n < 2; ++n) acc[a][b][m][n] = (f32x4){0.f, 0.f, 0.f, 0.f};
;         cur = nxt; cA = nA; cB = nB; ++ui;
.LBB0_1117:
	s_ashr_i32 s79, s78, 31
	s_lshl_b64 s[14:15], s[78:79], 19
	s_add_u32 s80, s40, s14
	s_addc_u32 s81, s41, s15
	s_and_b64 s[14:15], s[6:7], exec
	s_cselect_b32 s9, s81, s11
	s_cselect_b32 s18, s80, s10
	s_ashr_i32 s77, s76, 31
	s_lshl_b64 s[14:15], s[76:77], 19
	s_add_u32 s82, s0, s14
	s_addc_u32 s83, s1, s15
	s_and_b64 s[14:15], s[6:7], exec
	s_cselect_b32 s19, s83, s13
	s_cselect_b32 s58, s82, s12
	s_add_u32 s59, s12, 0x100
	v_mov_b32_e32 v0, 0
	s_addc_u32 s62, s13, 0
	s_mov_b32 s63, -2
	s_waitcnt lgkmcnt(0)
	v_mov_b32_e32 v1, v0
	v_mov_b32_e32 v2, v0
	v_mov_b32_e32 v3, v0
	v_mov_b32_e32 v16, v0
	v_mov_b32_e32 v17, v0
	v_mov_b32_e32 v18, v0
	v_mov_b32_e32 v19, v0
	v_mov_b32_e32 v4, v0
	v_mov_b32_e32 v5, v0
	v_mov_b32_e32 v6, v0
	v_mov_b32_e32 v7, v0
	v_mov_b32_e32 v20, v0
	v_mov_b32_e32 v21, v0
	v_mov_b32_e32 v22, v0
	v_mov_b32_e32 v23, v0
	v_mov_b32_e32 v8, v0
	v_mov_b32_e32 v9, v0
	v_mov_b32_e32 v10, v0
	v_mov_b32_e32 v11, v0
	v_mov_b32_e32 v24, v0
	v_mov_b32_e32 v25, v0
	v_mov_b32_e32 v26, v0
	v_mov_b32_e32 v27, v0
	v_mov_b32_e32 v12, v0
	v_mov_b32_e32 v13, v0
	v_mov_b32_e32 v14, v0
	v_mov_b32_e32 v15, v0
	v_mov_b32_e32 v28, v0
	v_mov_b32_e32 v29, v0
	v_mov_b32_e32 v30, v0
	v_mov_b32_e32 v31, v0
	v_mov_b32_e32 v32, v0
	v_mov_b32_e32 v33, v0
	v_mov_b32_e32 v34, v0
	v_mov_b32_e32 v35, v0
	v_mov_b32_e32 v48, v0
	v_mov_b32_e32 v49, v0
	v_mov_b32_e32 v50, v0
	v_mov_b32_e32 v51, v0
	v_mov_b32_e32 v36, v0
	v_mov_b32_e32 v37, v0
	v_mov_b32_e32 v38, v0
	v_mov_b32_e32 v39, v0
	v_mov_b32_e32 v52, v0
	v_mov_b32_e32 v53, v0
	v_mov_b32_e32 v54, v0
	v_mov_b32_e32 v55, v0
	v_mov_b32_e32 v40, v0
	v_mov_b32_e32 v41, v0
	v_mov_b32_e32 v42, v0
	v_mov_b32_e32 v43, v0
	v_mov_b32_e32 v56, v0
	v_mov_b32_e32 v57, v0
	v_mov_b32_e32 v58, v0
	v_mov_b32_e32 v59, v0
	v_mov_b32_e32 v44, v0
	v_mov_b32_e32 v45, v0
	v_mov_b32_e32 v46, v0
	v_mov_b32_e32 v47, v0
	v_mov_b32_e32 v60, v0
	v_mov_b32_e32 v61, v0
	v_mov_b32_e32 v62, v0
	v_mov_b32_e32 v63, v0
	v_mov_b32_e32 v64, v0
	v_mov_b32_e32 v65, v0
	v_mov_b32_e32 v66, v0
	v_mov_b32_e32 v67, v0
	v_mov_b32_e32 v80, v0
	v_mov_b32_e32 v81, v0
	v_mov_b32_e32 v82, v0
	v_mov_b32_e32 v83, v0
	v_mov_b32_e32 v68, v0
	v_mov_b32_e32 v69, v0
	v_mov_b32_e32 v70, v0
	v_mov_b32_e32 v71, v0
	v_mov_b32_e32 v84, v0
	v_mov_b32_e32 v85, v0
	v_mov_b32_e32 v86, v0
	v_mov_b32_e32 v87, v0
	v_mov_b32_e32 v72, v0
	v_mov_b32_e32 v73, v0
	v_mov_b32_e32 v74, v0
	v_mov_b32_e32 v75, v0
	v_mov_b32_e32 v88, v0
	v_mov_b32_e32 v89, v0
	v_mov_b32_e32 v90, v0
	v_mov_b32_e32 v91, v0
	v_mov_b32_e32 v76, v0
	v_mov_b32_e32 v77, v0
	v_mov_b32_e32 v78, v0
	v_mov_b32_e32 v79, v0
	v_mov_b32_e32 v92, v0
	v_mov_b32_e32 v93, v0
	v_mov_b32_e32 v94, v0
	v_mov_b32_e32 v95, v0
	v_mov_b32_e32 v96, v0
	v_mov_b32_e32 v97, v0
	v_mov_b32_e32 v98, v0
	v_mov_b32_e32 v99, v0
	v_mov_b32_e32 v112, v0
	v_mov_b32_e32 v113, v0
	v_mov_b32_e32 v114, v0
	v_mov_b32_e32 v115, v0
	v_mov_b32_e32 v100, v0
	v_mov_b32_e32 v101, v0
	v_mov_b32_e32 v102, v0
	v_mov_b32_e32 v103, v0
	v_mov_b32_e32 v116, v0
	v_mov_b32_e32 v117, v0
	v_mov_b32_e32 v118, v0
	v_mov_b32_e32 v119, v0
	v_mov_b32_e32 v104, v0
	v_mov_b32_e32 v105, v0
	v_mov_b32_e32 v106, v0
	v_mov_b32_e32 v107, v0
	v_mov_b32_e32 v120, v0
	v_mov_b32_e32 v121, v0
	v_mov_b32_e32 v122, v0
	v_mov_b32_e32 v123, v0
	v_mov_b32_e32 v108, v0
	v_mov_b32_e32 v109, v0
	v_mov_b32_e32 v110, v0
	v_mov_b32_e32 v111, v0
	v_mov_b32_e32 v124, v0
	v_mov_b32_e32 v125, v0
	v_mov_b32_e32 v126, v0
	v_mov_b32_e32 v127, v0
	.p2align 6

; __device__ __forceinline__ unsigned pk2(float lo, float hi) { f32x2_t v = {lo, hi}; bf16x2_t b = __builtin_convertvector(v, bf16x2_t); return __builtin_bit_cast(unsigned, b); }
; __device__ __forceinline__ float fexp2(float x) { return __builtin_amdgcn_exp2f(x); }
; #define MFMA(a, b, c) __builtin_amdgcn_mfma_f32_32x32x16_bf16((a), (b), (c), 0, 0, 0)
; template <int DQK, int DV>
; __device__ __forceinline__ void attn_pass2(const bf16_t* __restrict__ qh, const bf16_t* __restrict__ kh, const bf16_t* __restrict__ vth, int q0, char* smem, f32x16 (&o)[2][DV / 32], float kmax, int wvp) {
;     ...
;     f32x16 s[2][2];
;     const char* kb0 = sK + cur * KSB + kofs;
; #pragma unroll
;     for (int ks = 0; ks < NKS; ++ks) {
;       const bf16x8 a0 = *(const bf16x8*)(kb0 + ks * 32), a1 = *(const bf16x8*)(kb0 + 32 * KP + ks * 32);
; #pragma unroll
;       for (int qb = 0; qb < 2; ++qb) {
;         if (ks == 0) {
;           f32x16 z;
; #pragma unroll
;           for (int i = 0; i < 16; ++i) z[i] = 0.f;
;           s[qb][0] = MFMA(a0, qf[qb][0], z); s[qb][1] = MFMA(a1, qf[qb][0], z);
;         } else { s[qb][0] = MFMA(a0, qf[qb][ks], s[qb][0]); s[qb][1] = MFMA(a1, qf[qb][ks], s[qb][1]); }
;       }
;     }
;     __builtin_amdgcn_sched_barrier(0);
; #pragma unroll
;     for (int qb = 0; qb < 2; ++qb) {
;       float rs0 = 0.f, rs1 = 0.f;
; #pragma unroll
;       for (int i = 0; i < 16; ++i) { s[qb][0][i] = fexp2(s[qb][0][i] - mref[qb]); s[qb][1][i] = fexp2(s[qb][1][i] - mref[qb]); rs0 += s[qb][0][i]; rs1 += s[qb][1][i]; }
;       l_run[qb] += rs0 + rs1;
;     }
;     const char* vb0 = sV + cur * VSB + vofs;
; #pragma unroll
;     for (int kb = 0; kb < 2; ++kb)
; #pragma unroll
;       for (int s2 = 0; s2 < 2; ++s2) {
;         bf16x8 pq[2];
; #pragma unroll
;         for (int qb = 0; qb < 2; ++qb) {
;           u32x4 w;
;           w.x = pk2(s[qb][kb][8 * s2 + 0], s[qb][kb][8 * s2 + 1]); w.y = pk2(s[qb][kb][8 * s2 + 2], s[qb][kb][8 * s2 + 3]);
;           w.z = pk2(s[qb][kb][8 * s2 + 4], s[qb][kb][8 * s2 + 5]); w.w = pk2(s[qb][kb][8 * s2 + 6], s[qb][kb][8 * s2 + 7]);
;           pq[qb] = __builtin_bit_cast(bf16x8, w);
;         }
; #pragma unroll
;         for (int eb = 0; eb < NEB; ++eb) {
;           const bf16x8 a = *(const bf16x8*)(vb0 + eb * 32 * VP + (32 * kb + 16 * s2) * 2);
.LBB0_1429:
	s_mulk_i32 s7, 0x2400
	v_add_u32_e32 v180, s7, v169
	ds_read_b128 v[64:67], v180
	ds_read_b128 v[176:179], v180 offset:32
	ds_read_b128 v[68:71], v180 offset:4608
	ds_read_b128 v[192:195], v180 offset:4640
	s_add_i32 s6, s6, 1
	s_waitcnt lgkmcnt(3)
	v_mfma_f32_32x32x16_bf16 v[112:127], v[64:67], v[128:131], v[236:251]
	s_waitcnt lgkmcnt(1)
	v_mfma_f32_32x32x16_bf16 v[96:111], v[68:71], v[128:131], v[236:251]
	v_mfma_f32_32x32x16_bf16 v[80:95], v[64:67], v[144:147], v[236:251]
	v_mfma_f32_32x32x16_bf16 v[64:79], v[68:71], v[144:147], v[236:251]
	v_mfma_f32_32x32x16_bf16 v[112:127], v[176:179], v[132:135], v[112:127]
	s_waitcnt lgkmcnt(0)
	v_mfma_f32_32x32x16_bf16 v[96:111], v[192:195], v[132:135], v[96:111]
	v_mfma_f32_32x32x16_bf16 v[80:95], v[176:179], v[148:151], v[80:95]
	v_mfma_f32_32x32x16_bf16 v[64:79], v[192:195], v[148:151], v[64:79]
	ds_read_b128 v[176:179], v180 offset:64
	ds_read_b128 v[192:195], v180 offset:96
	ds_read_b128 v[196:199], v180 offset:4672
	ds_read_b128 v[200:203], v180 offset:4704
	s_waitcnt lgkmcnt(3)
	v_mfma_f32_32x32x16_bf16 v[112:127], v[176:179], v[136:139], v[112:127]
	s_waitcnt lgkmcnt(1)
	v_mfma_f32_32x32x16_bf16 v[96:111], v[196:199], v[136:139], v[96:111]
	v_mfma_f32_32x32x16_bf16 v[80:95], v[176:179], v[152:155], v[80:95]
	v_mfma_f32_32x32x16_bf16 v[64:79], v[196:199], v[152:155], v[64:79]
	v_mfma_f32_32x32x16_bf16 v[112:127], v[192:195], v[140:143], v[112:127]
	s_waitcnt lgkmcnt(0)
	v_mfma_f32_32x32x16_bf16 v[96:111], v[200:203], v[140:143], v[96:111]
	v_mfma_f32_32x32x16_bf16 v[80:95], v[192:195], v[156:159], v[80:95]
	v_mfma_f32_32x32x16_bf16 v[64:79], v[200:203], v[156:159], v[64:79]
	s_nop 9
	v_exp_f32_e32 v186, v96
	v_exp_f32_e32 v97, v97
	v_exp_f32_e32 v177, v112
	v_exp_f32_e32 v113, v113
	v_exp_f32_e32 v179, v114
	v_exp_f32_e32 v187, v98
	v_add_f32_e32 v98, v97, v186
	v_exp_f32_e32 v115, v115
	v_exp_f32_e32 v190, v99
	v_exp_f32_e32 v204, v100
	v_exp_f32_e32 v99, v116
	v_exp_f32_e32 v117, v117
	v_add_f32_e32 v96, v113, v177
	v_exp_f32_e32 v101, v101
	v_add_f32_e32 v96, v179, v96
	v_exp_f32_e32 v181, v118
	v_add_f32_e32 v96, v115, v96
	v_add_f32_e32 v96, v99, v96
	v_add_f32_e32 v96, v117, v96
	v_add_f32_e32 v112, v181, v96
	v_exp_f32_e32 v176, v119
	v_exp_f32_e32 v178, v103
	v_add_f32_e32 v98, v187, v98
	v_exp_f32_e32 v205, v102
	v_exp_f32_e32 v180, v120
	v_exp_f32_e32 v96, v104
	v_exp_f32_e32 v104, v123
	v_add_f32_e32 v98, v190, v98
	v_exp_f32_e32 v100, v106
	v_exp_f32_e32 v106, v107
	v_add_f32_e32 v98, v204, v98
	v_exp_f32_e32 v118, v124
	v_add_f32_e32 v98, v101, v98
	v_exp_f32_e32 v120, v108
	v_add_f32_e32 v102, v205, v98
	v_exp_f32_e32 v124, v125
	v_exp_f32_e32 v116, v121
	v_exp_f32_e32 v108, v109
	v_exp_f32_e32 v114, v105
	v_exp_f32_e32 v98, v122
	v_exp_f32_e32 v122, v126
	v_exp_f32_e32 v110, v110
	v_exp_f32_e32 v126, v127
	v_exp_f32_e32 v103, v80
	v_exp_f32_e32 v107, v64
	v_exp_f32_e32 v109, v81
	v_exp_f32_e32 v65, v65
	v_exp_f32_e32 v121, v66
	v_add_f32_e32 v66, v109, v103
	v_add_f32_e32 v80, v65, v107
	v_add_f32_e32 v206, v121, v80
	v_exp_f32_e32 v207, v83
	v_add_u32_e32 v209, s7, v185
	v_exp_f32_e32 v64, v111
	v_exp_f32_e32 v111, v82
	v_exp_f32_e32 v208, v84
	ds_read_b128 v[80:83], v209 offset:18432
	ds_read_b128 v[196:199], v209 offset:18464
	ds_read_b128 v[200:203], v209 offset:23040
	v_exp_f32_e32 v212, v85
	v_exp_f32_e32 v213, v86
	v_cvt_pk_bf16_f32 v192, v177, v113
	v_exp_f32_e32 v177, v87
	v_cvt_pk_bf16_f32 v84, v103, v109
	v_exp_f32_e32 v109, v67
	v_add_f32_e32 v66, v111, v66
	v_cvt_pk_bf16_f32 v85, v111, v207
	v_exp_f32_e32 v111, v68
	v_cvt_pk_bf16_f32 v195, v181, v176
	v_exp_f32_e32 v181, v88
	v_cvt_pk_bf16_f32 v194, v99, v117
	v_exp_f32_e32 v117, v89
	v_cvt_pk_bf16_f32 v193, v179, v115
	v_cvt_pk_bf16_f32 v86, v208, v212
	v_cvt_pk_bf16_f32 v87, v213, v177
	v_exp_f32_e32 v99, v90
	s_waitcnt lgkmcnt(2)
	v_mfma_f32_32x32x16_bf16 v[48:63], v[80:83], v[192:195], v[48:63]
	v_exp_f32_e32 v105, v91
	v_exp_f32_e32 v119, v92
	v_exp_f32_e32 v125, v93
	v_mfma_f32_32x32x16_bf16 v[16:31], v[80:83], v[84:87], v[16:31]
	ds_read_b128 v[80:83], v209 offset:23072
	v_exp_f32_e32 v123, v94
	v_exp_f32_e32 v92, v69
	v_exp_f32_e32 v127, v95
	s_waitcnt lgkmcnt(1)
; __device__ __forceinline__ unsigned pk2(float lo, float hi) { f32x2_t v = {lo, hi}; bf16x2_t b = __builtin_convertvector(v, bf16x2_t); return __builtin_bit_cast(unsigned, b); }
; __device__ __forceinline__ float fexp2(float x) { return __builtin_amdgcn_exp2f(x); }
; #define MFMA(a, b, c) __builtin_amdgcn_mfma_f32_32x32x16_bf16((a), (b), (c), 0, 0, 0)
; template <int DQK, int DV>
; __device__ __forceinline__ void attn_pass2(const bf16_t* __restrict__ qh, const bf16_t* __restrict__ kh, const bf16_t* __restrict__ vth, int q0, char* smem, f32x16 (&o)[2][DV / 32], float kmax, int wvp) {
;     ...
; #pragma unroll
;     for (int qb = 0; qb < 2; ++qb) {
;       float rs0 = 0.f, rs1 = 0.f;
; #pragma unroll
;       for (int i = 0; i < 16; ++i) { s[qb][0][i] = fexp2(s[qb][0][i] - mref[qb]); s[qb][1][i] = fexp2(s[qb][1][i] - mref[qb]); rs0 += s[qb][0][i]; rs1 += s[qb][1][i]; }
;       l_run[qb] += rs0 + rs1;
;     }
;     const char* vb0 = sV + cur * VSB + vofs;
; #pragma unroll
;     for (int kb = 0; kb < 2; ++kb)
; #pragma unroll
;       for (int s2 = 0; s2 < 2; ++s2) {
;         bf16x8 pq[2];
; #pragma unroll
;         for (int qb = 0; qb < 2; ++qb) {
;           u32x4 w;
;           w.x = pk2(s[qb][kb][8 * s2 + 0], s[qb][kb][8 * s2 + 1]); w.y = pk2(s[qb][kb][8 * s2 + 2], s[qb][kb][8 * s2 + 3]);
;           w.z = pk2(s[qb][kb][8 * s2 + 4], s[qb][kb][8 * s2 + 5]); w.w = pk2(s[qb][kb][8 * s2 + 6], s[qb][kb][8 * s2 + 7]);
;           pq[qb] = __builtin_bit_cast(bf16x8, w);
;         }
; #pragma unroll
;         for (int eb = 0; eb < NEB; ++eb) {
;           const bf16x8 a = *(const bf16x8*)(vb0 + eb * 32 * VP + (32 * kb + 16 * s2) * 2);
; #pragma unroll
;           for (int qb = 0; qb < 2; ++qb) o[qb][eb] = MFMA(a, pq[qb], o[qb][eb]);
;         }
;       }
;   }
	v_mfma_f32_32x32x16_bf16 v[0:15], v[200:203], v[84:87], v[0:15]
	v_exp_f32_e32 v93, v70
	v_add_f32_e32 v66, v207, v66
	v_add_f32_e32 v67, v109, v206
	v_add_f32_e32 v66, v208, v66
	v_add_f32_e32 v67, v111, v67
	v_add_f32_e32 v66, v212, v66
	v_add_f32_e32 v67, v92, v67
	v_mfma_f32_32x32x16_bf16 v[32:47], v[200:203], v[192:195], v[32:47]
	v_cvt_pk_bf16_f32 v84, v180, v116
	v_cvt_pk_bf16_f32 v85, v98, v104
	v_cvt_pk_bf16_f32 v86, v118, v124
	v_cvt_pk_bf16_f32 v87, v122, v126
	v_cvt_pk_bf16_f32 v88, v181, v117
	v_cvt_pk_bf16_f32 v89, v99, v105
	v_cvt_pk_bf16_f32 v90, v119, v125
	v_cvt_pk_bf16_f32 v91, v123, v127
	v_add_f32_e32 v113, v213, v66
	v_add_f32_e32 v103, v93, v67
	ds_read_b128 v[66:69], v209 offset:18496
	v_mfma_f32_32x32x16_bf16 v[48:63], v[196:199], v[84:87], v[48:63]
	v_exp_f32_e32 v179, v71
	v_mov_b32_e32 v70, v72
	v_exp_f32_e32 v115, v73
	v_cvt_pk_bf16_f32 v71, v121, v109
	v_cvt_pk_bf16_f32 v72, v111, v92
	v_cvt_pk_bf16_f32 v73, v93, v179
	v_mfma_f32_32x32x16_bf16 v[16:31], v[196:199], v[88:91], v[16:31]
	v_lshl_add_u64 v[170:171], v[170:171], 0, s[52:53]
	s_cmpk_lg_i32 s6, 0x80
	v_lshl_add_u64 v[172:173], v[172:173], 0, s[54:55]
	s_waitcnt lgkmcnt(1)
	v_mfma_f32_32x32x16_bf16 v[0:15], v[80:83], v[88:91], v[0:15]
	ds_read_b128 v[88:91], v209 offset:23104
	v_mfma_f32_32x32x16_bf16 v[32:47], v[80:83], v[84:87], v[32:47]
	v_cvt_pk_bf16_f32 v80, v186, v97
	v_exp_f32_e32 v97, v70
	v_cvt_pk_bf16_f32 v70, v107, v65
	v_cvt_pk_bf16_f32 v81, v187, v190
	v_cvt_pk_bf16_f32 v82, v204, v101
	v_cvt_pk_bf16_f32 v83, v205, v178
	v_exp_f32_e32 v101, v74
	ds_read_b128 v[84:87], v209 offset:18528
	s_waitcnt lgkmcnt(2)
	v_mfma_f32_32x32x16_bf16 v[48:63], v[66:69], v[80:83], v[48:63]
	v_exp_f32_e32 v107, v75
	v_exp_f32_e32 v121, v76
	v_exp_f32_e32 v109, v77
	v_exp_f32_e32 v111, v78
	v_mfma_f32_32x32x16_bf16 v[16:31], v[66:69], v[70:73], v[16:31]
	ds_read_b128 v[66:69], v209 offset:23136
	v_exp_f32_e32 v65, v79
	v_add_f32_e32 v74, v178, v102
	v_add_f32_e32 v75, v179, v103
	s_nop 0
	v_add_f32_e32 v74, v96, v74
	v_add_f32_e32 v75, v97, v75
	s_waitcnt lgkmcnt(2)
	v_mfma_f32_32x32x16_bf16 v[32:47], v[88:91], v[80:83], v[32:47]
	v_add_f32_e64 v80, v114, v74
	v_add_f32_e64 v81, v115, v75
	v_cvt_pk_bf16_f32 v74, v97, v115
	v_cvt_pk_bf16_f32 v75, v101, v107
	v_add_f32_e64 v80, v100, v80
	v_add_f32_e64 v81, v101, v81
	v_add_f32_e32 v80, v106, v80
	v_add_f32_e32 v81, v107, v81
	v_mfma_f32_32x32x16_bf16 v[0:15], v[88:91], v[70:73], v[0:15]
	v_add_f32_e64 v70, v176, v112
	v_add_f32_e64 v71, v177, v113
	v_cvt_pk_bf16_f32 v72, v120, v108
	v_add_f32_e64 v76, v180, v70
	v_add_f32_e64 v77, v181, v71
	v_cvt_pk_bf16_f32 v70, v96, v114
	v_cvt_pk_bf16_f32 v71, v100, v106
	v_cvt_pk_bf16_f32 v73, v110, v64
	v_add_f32_e32 v78, v116, v76
	v_add_f32_e32 v79, v117, v77
	v_cvt_pk_bf16_f32 v76, v121, v109
	v_cvt_pk_bf16_f32 v77, v111, v65
	s_waitcnt lgkmcnt(1)
	v_mfma_f32_32x32x16_bf16 v[48:63], v[84:87], v[70:73], v[48:63]
	v_add_f32_e64 v78, v98, v78
	v_add_f32_e64 v79, v99, v79
	v_add_f32_e64 v80, v120, v80
	v_add_f32_e64 v81, v121, v81
	v_add_f32_e64 v78, v104, v78
	v_add_f32_e64 v79, v105, v79
	v_add_f32_e32 v78, v118, v78
	v_add_f32_e32 v79, v119, v79
	s_nop 0
	v_add_f32_e32 v78, v124, v78
	v_add_f32_e32 v79, v125, v79
	v_mfma_f32_32x32x16_bf16 v[16:31], v[84:87], v[74:77], v[16:31]
	s_waitcnt lgkmcnt(0)
	v_mfma_f32_32x32x16_bf16 v[32:47], v[66:69], v[70:73], v[32:47]
	v_add_f32_e64 v70, v108, v80
	v_add_f32_e64 v71, v109, v81
	v_add_f32_e64 v72, v122, v78
	v_add_f32_e64 v73, v123, v79
	v_add_f32_e64 v70, v110, v70
	v_add_f32_e64 v71, v111, v71
	v_add_f32_e32 v72, v126, v72
	v_add_f32_e32 v73, v127, v73
	v_add_f32_e32 v64, v64, v70
	v_add_f32_e32 v65, v65, v71
	s_nop 0
	v_add_f32_e32 v64, v72, v64
	v_add_f32_e32 v65, v73, v65
	v_mfma_f32_32x32x16_bf16 v[0:15], v[66:69], v[74:77], v[0:15]
	v_add_f32_e64 v174, v174, v64
	v_add_f32_e64 v175, v175, v65
	s_cbranch_scc0 .LBB0_1433
	.p2align 6

; __device__ __forceinline__ unsigned pk2(float lo, float hi) { f32x2_t v = {lo, hi}; bf16x2_t b = __builtin_convertvector(v, bf16x2_t); return __builtin_bit_cast(unsigned, b); }
; __device__ __forceinline__ float fexp2(float x) { return __builtin_amdgcn_exp2f(x); }
; #define MFMA(a, b, c) __builtin_amdgcn_mfma_f32_32x32x16_bf16((a), (b), (c), 0, 0, 0)
; template <int DQK, int DV>
; __device__ __forceinline__ void attn_pass2(const bf16_t* __restrict__ qh, const bf16_t* __restrict__ kh, const bf16_t* __restrict__ vth, int q0, char* smem, f32x16 (&o)[2][DV / 32], float kmax, int wvp) {
;     ...
;     f32x16 s[2][2];
;     const char* kb0 = sK + cur * KSB + kofs;
; #pragma unroll
;     for (int ks = 0; ks < NKS; ++ks) {
;       const bf16x8 a0 = *(const bf16x8*)(kb0 + ks * 32), a1 = *(const bf16x8*)(kb0 + 32 * KP + ks * 32);
; #pragma unroll
;       for (int qb = 0; qb < 2; ++qb) {
;         if (ks == 0) {
;           f32x16 z;
; #pragma unroll
;           for (int i = 0; i < 16; ++i) z[i] = 0.f;
;           s[qb][0] = MFMA(a0, qf[qb][0], z); s[qb][1] = MFMA(a1, qf[qb][0], z);
;         } else { s[qb][0] = MFMA(a0, qf[qb][ks], s[qb][0]); s[qb][1] = MFMA(a1, qf[qb][ks], s[qb][1]); }
;       }
;     }
;     __builtin_amdgcn_sched_barrier(0);
; #pragma unroll
;     for (int qb = 0; qb < 2; ++qb) {
;       float rs0 = 0.f, rs1 = 0.f;
; #pragma unroll
;       for (int i = 0; i < 16; ++i) { s[qb][0][i] = fexp2(s[qb][0][i] - mref[qb]); s[qb][1][i] = fexp2(s[qb][1][i] - mref[qb]); rs0 += s[qb][0][i]; rs1 += s[qb][1][i]; }
;       l_run[qb] += rs0 + rs1;
;     }
;     const char* vb0 = sV + cur * VSB + vofs;
; #pragma unroll
;     for (int kb = 0; kb < 2; ++kb)
; #pragma unroll
;       for (int s2 = 0; s2 < 2; ++s2) {
;         bf16x8 pq[2];
; #pragma unroll
;         for (int qb = 0; qb < 2; ++qb) {
;           u32x4 w;
;           w.x = pk2(s[qb][kb][8 * s2 + 0], s[qb][kb][8 * s2 + 1]); w.y = pk2(s[qb][kb][8 * s2 + 2], s[qb][kb][8 * s2 + 3]);
;           w.z = pk2(s[qb][kb][8 * s2 + 4], s[qb][kb][8 * s2 + 5]); w.w = pk2(s[qb][kb][8 * s2 + 6], s[qb][kb][8 * s2 + 7]);
;           pq[qb] = __builtin_bit_cast(bf16x8, w);
;         }
; #pragma unroll
;         for (int eb = 0; eb < NEB; ++eb) {
;           const bf16x8 a = *(const bf16x8*)(vb0 + eb * 32 * VP + (32 * kb + 16 * s2) * 2);
.LBB0_1445:
	s_mul_i32 s8, s11, 0x3400
	v_add_u32_e32 v190, s8, v215
	ds_read_b128 v[64:67], v190
	ds_read_b128 v[202:205], v190 offset:32
	ds_read_b128 v[68:71], v190 offset:6656
	ds_read_b128 v[206:209], v190 offset:6688
	s_waitcnt lgkmcnt(3)
	v_mfma_f32_32x32x16_bf16 v[112:127], v[64:67], v[128:131], v[236:251]
	s_waitcnt lgkmcnt(1)
	v_mfma_f32_32x32x16_bf16 v[96:111], v[68:71], v[128:131], v[236:251]
	v_mfma_f32_32x32x16_bf16 v[80:95], v[64:67], v[152:155], v[236:251]
	v_mfma_f32_32x32x16_bf16 v[64:79], v[68:71], v[152:155], v[236:251]
	v_mfma_f32_32x32x16_bf16 v[112:127], v[202:205], v[132:135], v[112:127]
	s_waitcnt lgkmcnt(0)
	v_mfma_f32_32x32x16_bf16 v[96:111], v[206:209], v[132:135], v[96:111]
	v_mfma_f32_32x32x16_bf16 v[80:95], v[202:205], v[156:159], v[80:95]
	v_mfma_f32_32x32x16_bf16 v[64:79], v[206:209], v[156:159], v[64:79]
	ds_read_b128 v[202:205], v190 offset:64
	ds_read_b128 v[206:209], v190 offset:96
	ds_read_b128 v[218:221], v190 offset:6720
	ds_read_b128 v[222:225], v190 offset:6752
	s_waitcnt lgkmcnt(3)
	v_mfma_f32_32x32x16_bf16 v[112:127], v[202:205], v[136:139], v[112:127]
	s_waitcnt lgkmcnt(1)
	v_mfma_f32_32x32x16_bf16 v[96:111], v[218:221], v[136:139], v[96:111]
	v_mfma_f32_32x32x16_bf16 v[80:95], v[202:205], v[160:163], v[80:95]
	v_mfma_f32_32x32x16_bf16 v[64:79], v[218:221], v[160:163], v[64:79]
	v_mfma_f32_32x32x16_bf16 v[112:127], v[206:209], v[140:143], v[112:127]
	s_waitcnt lgkmcnt(0)
	v_mfma_f32_32x32x16_bf16 v[96:111], v[222:225], v[140:143], v[96:111]
	v_mfma_f32_32x32x16_bf16 v[80:95], v[206:209], v[164:167], v[80:95]
	ds_read_b128 v[202:205], v190 offset:128
	ds_read_b128 v[206:209], v190 offset:160
	v_mfma_f32_32x32x16_bf16 v[64:79], v[222:225], v[164:167], v[64:79]
	ds_read_b128 v[218:221], v190 offset:6784
	ds_read_b128 v[222:225], v190 offset:6816
	s_waitcnt lgkmcnt(3)
	v_mfma_f32_32x32x16_bf16 v[112:127], v[202:205], v[144:147], v[112:127]
	s_waitcnt lgkmcnt(1)
	v_mfma_f32_32x32x16_bf16 v[96:111], v[218:221], v[144:147], v[96:111]
	v_mfma_f32_32x32x16_bf16 v[80:95], v[202:205], v[168:171], v[80:95]
	v_mfma_f32_32x32x16_bf16 v[64:79], v[218:221], v[168:171], v[64:79]
	v_mfma_f32_32x32x16_bf16 v[112:127], v[206:209], v[148:151], v[112:127]
	s_waitcnt lgkmcnt(0)
	v_mfma_f32_32x32x16_bf16 v[96:111], v[222:225], v[148:151], v[96:111]
	v_mfma_f32_32x32x16_bf16 v[80:95], v[206:209], v[172:175], v[80:95]
	v_mfma_f32_32x32x16_bf16 v[64:79], v[222:225], v[172:175], v[64:79]
	s_nop 9
	v_exp_f32_e32 v96, v96
	v_exp_f32_e32 v112, v112
	v_exp_f32_e32 v208, v97
	v_exp_f32_e32 v204, v113
	v_exp_f32_e32 v227, v99
	v_exp_f32_e32 v114, v114
	v_exp_f32_e32 v116, v116
	v_exp_f32_e32 v217, v98
	v_exp_f32_e32 v100, v100
	v_add_f32_e32 v98, v208, v96
	v_exp_f32_e32 v202, v117
	v_add_f32_e32 v97, v204, v112
	v_exp_f32_e32 v190, v115
	v_exp_f32_e32 v228, v101
	v_exp_f32_e32 v118, v118
	v_add_f32_e32 v98, v217, v98
	v_exp_f32_e32 v229, v102
	v_add_f32_e32 v97, v114, v97
	v_add_f32_e32 v98, v227, v98
	v_add_f32_e32 v97, v190, v97
	v_add_f32_e32 v98, v100, v98
	v_add_f32_e32 v97, v116, v97
	v_add_f32_e32 v98, v228, v98
	v_add_f32_e32 v97, v202, v97
	v_add_f32_e32 v113, v229, v98
	v_add_f32_e32 v115, v118, v97
	v_exp_f32_e32 v203, v119
	v_exp_f32_e32 v119, v121
	v_exp_f32_e32 v117, v105
	v_exp_f32_e32 v99, v122
	v_exp_f32_e32 v101, v106
	v_exp_f32_e32 v205, v103
	v_exp_f32_e32 v103, v123
	v_exp_f32_e32 v105, v107
	v_exp_f32_e32 v107, v124
	v_exp_f32_e32 v121, v108
	v_exp_f32_e32 v125, v125
	v_exp_f32_e32 v109, v109
	v_exp_f32_e32 v123, v126
	v_exp_f32_e32 v209, v110
	v_exp_f32_e32 v127, v127
	v_exp_f32_e32 v98, v80
	v_exp_f32_e32 v102, v81
	v_exp_f32_e32 v108, v65
	v_exp_f32_e32 v207, v120
	v_exp_f32_e32 v97, v104
	v_exp_f32_e32 v104, v64
	v_exp_f32_e32 v106, v82
	v_exp_f32_e32 v111, v111
	v_exp_f32_e32 v110, v66
	v_add_f32_e32 v64, v102, v98
	v_add_f32_e32 v120, v106, v64
	s_mulk_i32 s11, 0x2400
	v_add_f32_e32 v65, v108, v104
	v_exp_f32_e32 v231, v83
	v_add_u32_e32 v233, s11, v216
	v_add_f32_e32 v230, v110, v65
	v_mov_b32_e32 v122, v67
	v_exp_f32_e32 v232, v84
	ds_read_b128 v[64:67], v233 offset:26624
	ds_read_b128 v[218:221], v233 offset:26656
	v_exp_f32_e32 v234, v85
	ds_read_b128 v[222:225], v233 offset:31232
	v_exp_f32_e32 v235, v86
	v_cvt_pk_bf16_f32 v82, v116, v202
	v_exp_f32_e32 v202, v87
	v_cvt_pk_bf16_f32 v80, v112, v204
	v_cvt_pk_bf16_f32 v81, v114, v190
	v_cvt_pk_bf16_f32 v83, v118, v203
	v_cvt_pk_bf16_f32 v84, v98, v102
	v_cvt_pk_bf16_f32 v85, v106, v231
	v_cvt_pk_bf16_f32 v86, v232, v234
	v_cvt_pk_bf16_f32 v87, v235, v202
	s_waitcnt lgkmcnt(2)
; __device__ __forceinline__ unsigned pk2(float lo, float hi) { f32x2_t v = {lo, hi}; bf16x2_t b = __builtin_convertvector(v, bf16x2_t); return __builtin_bit_cast(unsigned, b); }
; __device__ __forceinline__ float fexp2(float x) { return __builtin_amdgcn_exp2f(x); }
; #define MFMA(a, b, c) __builtin_amdgcn_mfma_f32_32x32x16_bf16((a), (b), (c), 0, 0, 0)
; template <int DQK, int DV>
; __device__ __forceinline__ void attn_pass2(const bf16_t* __restrict__ qh, const bf16_t* __restrict__ kh, const bf16_t* __restrict__ vth, int q0, char* smem, f32x16 (&o)[2][DV / 32], float kmax, int wvp) {
;     ...
; #pragma unroll
;     for (int qb = 0; qb < 2; ++qb) {
;       float rs0 = 0.f, rs1 = 0.f;
; #pragma unroll
;       for (int i = 0; i < 16; ++i) { s[qb][0][i] = fexp2(s[qb][0][i] - mref[qb]); s[qb][1][i] = fexp2(s[qb][1][i] - mref[qb]); rs0 += s[qb][0][i]; rs1 += s[qb][1][i]; }
;       l_run[qb] += rs0 + rs1;
;     }
;     const char* vb0 = sV + cur * VSB + vofs;
; #pragma unroll
;     for (int kb = 0; kb < 2; ++kb)
; #pragma unroll
;       for (int s2 = 0; s2 < 2; ++s2) {
;         bf16x8 pq[2];
; #pragma unroll
;         for (int qb = 0; qb < 2; ++qb) {
;           u32x4 w;
;           w.x = pk2(s[qb][kb][8 * s2 + 0], s[qb][kb][8 * s2 + 1]); w.y = pk2(s[qb][kb][8 * s2 + 2], s[qb][kb][8 * s2 + 3]);
;           w.z = pk2(s[qb][kb][8 * s2 + 4], s[qb][kb][8 * s2 + 5]); w.w = pk2(s[qb][kb][8 * s2 + 6], s[qb][kb][8 * s2 + 7]);
;           pq[qb] = __builtin_bit_cast(bf16x8, w);
;         }
; #pragma unroll
;         for (int eb = 0; eb < NEB; ++eb) {
;           const bf16x8 a = *(const bf16x8*)(vb0 + eb * 32 * VP + (32 * kb + 16 * s2) * 2);
; #pragma unroll
;           for (int qb = 0; qb < 2; ++qb) o[qb][eb] = MFMA(a, pq[qb], o[qb][eb]);
;         }
;       }
;   }
	v_mfma_f32_32x32x16_bf16 v[48:63], v[64:67], v[80:83], v[48:63]
	v_exp_f32_e32 v116, v122
	s_add_u32 s6, s6, 0x3000
	s_addc_u32 s7, s7, 0
	s_add_i32 s10, s10, 1
	v_mfma_f32_32x32x16_bf16 v[16:31], v[64:67], v[84:87], v[16:31]
	v_exp_f32_e32 v190, v68
	v_exp_f32_e32 v206, v88
	ds_read_b128 v[64:67], v233 offset:31264
	v_exp_f32_e32 v118, v89
	s_waitcnt lgkmcnt(1)
	v_mfma_f32_32x32x16_bf16 v[32:47], v[222:225], v[80:83], v[32:47]
	v_exp_f32_e32 v98, v90
	v_exp_f32_e32 v102, v91
	v_exp_f32_e32 v106, v92
	v_exp_f32_e32 v124, v93
	v_mfma_f32_32x32x16_bf16 v[0:15], v[222:225], v[84:87], v[0:15]
	v_exp_f32_e32 v122, v94
	v_exp_f32_e32 v89, v69
	v_exp_f32_e32 v126, v95
	v_exp_f32_e32 v90, v70
	v_cvt_pk_bf16_f32 v80, v207, v119
	v_cvt_pk_bf16_f32 v81, v99, v103
	v_cvt_pk_bf16_f32 v82, v107, v125
	v_cvt_pk_bf16_f32 v83, v123, v127
	v_add_f32_e32 v68, v231, v120
	v_add_f32_e32 v88, v116, v230
	v_mfma_f32_32x32x16_bf16 v[48:63], v[218:221], v[80:83], v[48:63]
	v_add_f32_e32 v68, v232, v68
	v_add_f32_e32 v88, v190, v88
	v_add_f32_e32 v68, v234, v68
	v_add_f32_e32 v69, v89, v88
	v_cvt_pk_bf16_f32 v84, v206, v118
	v_cvt_pk_bf16_f32 v85, v98, v102
	v_cvt_pk_bf16_f32 v86, v106, v124
	s_waitcnt lgkmcnt(0)
	v_mfma_f32_32x32x16_bf16 v[32:47], v[64:67], v[80:83], v[32:47]
	v_exp_f32_e32 v204, v71
	v_cvt_pk_bf16_f32 v87, v122, v126
	v_add_f32_e32 v114, v235, v68
	v_add_f32_e32 v112, v90, v69
	ds_read_b128 v[68:71], v233 offset:26688
	ds_read_b128 v[80:83], v233 offset:26720
	v_mfma_f32_32x32x16_bf16 v[16:31], v[218:221], v[84:87], v[16:31]
	s_cmp_lg_u32 s6, 0x180000
	v_lshl_add_u64 v[194:195], v[194:195], 0, s[54:55]
	v_mfma_f32_32x32x16_bf16 v[0:15], v[64:67], v[84:87], v[0:15]
	v_cvt_pk_bf16_f32 v86, v190, v89
	v_cvt_pk_bf16_f32 v87, v90, v204
	ds_read_b128 v[88:91], v233 offset:31296
	v_cvt_pk_bf16_f32 v64, v96, v208
	v_cvt_pk_bf16_f32 v65, v217, v227
	v_cvt_pk_bf16_f32 v66, v100, v228
	v_cvt_pk_bf16_f32 v67, v229, v205
	v_cvt_pk_bf16_f32 v84, v104, v108
	v_cvt_pk_bf16_f32 v85, v110, v116
	s_waitcnt lgkmcnt(2)
	v_mfma_f32_32x32x16_bf16 v[48:63], v[68:71], v[64:67], v[48:63]
	v_exp_f32_e32 v96, v72
	v_exp_f32_e32 v116, v73
	v_exp_f32_e32 v120, v76
	v_add_f32_e32 v72, v204, v112
	v_add_f32_e32 v73, v205, v113
	v_mfma_f32_32x32x16_bf16 v[16:31], v[68:71], v[84:87], v[16:31]
	v_exp_f32_e32 v100, v74
	v_exp_f32_e32 v104, v75
	ds_read_b128 v[68:71], v233 offset:31328
	v_add_f32_e32 v72, v96, v72
	v_add_f32_e32 v73, v97, v73
	s_waitcnt lgkmcnt(1)
	v_mfma_f32_32x32x16_bf16 v[32:47], v[88:91], v[64:67], v[32:47]
	v_exp_f32_e32 v108, v77
	v_exp_f32_e32 v208, v78
	v_exp_f32_e32 v110, v79
	v_add_f32_e32 v64, v202, v114
	v_add_f32_e32 v65, v203, v115
	v_mfma_f32_32x32x16_bf16 v[0:15], v[88:91], v[84:87], v[0:15]
	v_add_f32_e64 v74, v206, v64
	v_add_f32_e64 v75, v207, v65
	v_cvt_pk_bf16_f32 v64, v97, v117
	v_cvt_pk_bf16_f32 v65, v101, v105
	v_cvt_pk_bf16_f32 v66, v121, v109
	v_cvt_pk_bf16_f32 v67, v209, v111
	v_add_f32_e32 v76, v118, v74
	v_add_f32_e32 v77, v119, v75
	v_add_f32_e32 v78, v116, v72
	v_add_f32_e32 v79, v117, v73
	v_cvt_pk_bf16_f32 v72, v96, v116
	v_cvt_pk_bf16_f32 v73, v100, v104
	v_cvt_pk_bf16_f32 v74, v120, v108
	v_cvt_pk_bf16_f32 v75, v208, v110
	v_mfma_f32_32x32x16_bf16 v[48:63], v[80:83], v[64:67], v[48:63]
	v_add_f32_e64 v76, v98, v76
	v_add_f32_e64 v77, v99, v77
	v_add_f32_e64 v78, v100, v78
	v_add_f32_e64 v79, v101, v79
	v_add_f32_e64 v76, v102, v76
	v_add_f32_e64 v77, v103, v77
	v_add_f32_e32 v78, v104, v78
	v_add_f32_e32 v79, v105, v79
	v_add_f32_e32 v76, v106, v76
	v_add_f32_e32 v77, v107, v77
	v_add_f32_e32 v78, v120, v78
	v_add_f32_e32 v79, v121, v79
	v_add_f32_e32 v76, v124, v76
	v_add_f32_e32 v77, v125, v77
	v_mfma_f32_32x32x16_bf16 v[16:31], v[80:83], v[72:75], v[16:31]
	s_waitcnt lgkmcnt(0)
	v_mfma_f32_32x32x16_bf16 v[32:47], v[68:71], v[64:67], v[32:47]
	v_add_f32_e64 v64, v108, v78
	v_add_f32_e64 v65, v109, v79
	v_add_f32_e64 v66, v122, v76
	v_add_f32_e64 v67, v123, v77
	v_add_f32_e64 v64, v208, v64
	v_add_f32_e64 v65, v209, v65
	v_add_f32_e32 v66, v126, v66
	v_add_f32_e32 v67, v127, v67
	v_add_f32_e32 v64, v110, v64
	v_add_f32_e32 v65, v111, v65
	s_nop 0
	v_add_f32_e32 v64, v66, v64
	v_add_f32_e32 v65, v67, v65
	v_mfma_f32_32x32x16_bf16 v[0:15], v[68:71], v[72:75], v[0:15]
	v_add_f32_e64 v200, v200, v64
	v_add_f32_e64 v201, v201, v65
	s_cbranch_scc0 .LBB0_1425
	.p2align 6

; template <class Epi, class Sched, bool ALIGN_EPI = false, bool SP2 = false, bool F16 = false, bool TOKPERM = false>
; __device__ __forceinline__ void gemm_phase(PG8_LAS unsigned char* lds, const Gemm g, const Sched& S, const Epi& E, int wv) {
;     ...
;         const bool has_next = S.next(ui + 1, nxt);
;         const char* nA = has_next ? (const char*)g.A + (size_t)nxt.pm * tstep : cA; const char* nB = has_next ? (const char*)g.Bt + (size_t)nxt.pn * tstep : cB;
;     ...
; #pragma unroll
;         for (int a = 0; a < 2; ++a)
; #pragma unroll
;             for (int b = 0; b < 2; ++b)
; #pragma unroll
;                 for (int m = 0; m < 4; ++m)
; #pragma unroll
;                     for (int n = 0; n < 2; ++n) acc[a][b][m][n] = (f32x4){0.f, 0.f, 0.f, 0.f};
;         cur = nxt; cA = nA; cB = nB; ++ui;
.LBB0_1523:
	s_ashr_i32 s15, s14, 31
	v_cmp_lt_i64_e32 vcc, s[16:17], v[142:143]
	s_lshl_b64 s[16:17], s[14:15], 19
	s_add_u32 s16, s30, s16
	s_addc_u32 s17, s31, s17
	s_and_b64 s[18:19], vcc, exec
	s_cselect_b32 s15, s17, s25
	s_cselect_b32 s21, s16, s24
	s_ashr_i32 s13, s12, 31
	s_lshl_b64 s[18:19], s[12:13], 19
	s_add_u32 s18, s1, s18
	s_addc_u32 s19, s2, s19
	s_and_b64 s[46:47], vcc, exec
	s_cselect_b32 s13, s19, s45
	s_cselect_b32 s62, s18, s44
	s_add_u32 s24, s24, 0x40080
	s_addc_u32 s25, s25, 0
	s_add_u32 s63, s44, 0x100
	v_mov_b32_e32 v0, 0
	s_addc_u32 s64, s45, 0
	s_mov_b32 s65, -2
	s_waitcnt lgkmcnt(0)
	v_mov_b32_e32 v1, v0
	v_mov_b32_e32 v2, v0
	v_mov_b32_e32 v3, v0
	v_mov_b32_e32 v4, v0
	v_mov_b32_e32 v5, v0
	v_mov_b32_e32 v6, v0
	v_mov_b32_e32 v7, v0
	v_mov_b32_e32 v16, v0
	v_mov_b32_e32 v17, v0
	v_mov_b32_e32 v18, v0
	v_mov_b32_e32 v19, v0
	v_mov_b32_e32 v20, v0
	v_mov_b32_e32 v21, v0
	v_mov_b32_e32 v22, v0
	v_mov_b32_e32 v23, v0
	v_mov_b32_e32 v32, v0
	v_mov_b32_e32 v33, v0
	v_mov_b32_e32 v34, v0
	v_mov_b32_e32 v35, v0
	v_mov_b32_e32 v36, v0
	v_mov_b32_e32 v37, v0
	v_mov_b32_e32 v38, v0
	v_mov_b32_e32 v39, v0
	v_mov_b32_e32 v48, v0
	v_mov_b32_e32 v49, v0
	v_mov_b32_e32 v50, v0
	v_mov_b32_e32 v51, v0
	v_mov_b32_e32 v52, v0
	v_mov_b32_e32 v53, v0
	v_mov_b32_e32 v54, v0
	v_mov_b32_e32 v55, v0
	v_mov_b32_e32 v8, v0
	v_mov_b32_e32 v9, v0
	v_mov_b32_e32 v10, v0
	v_mov_b32_e32 v11, v0
	v_mov_b32_e32 v12, v0
	v_mov_b32_e32 v13, v0
	v_mov_b32_e32 v14, v0
	v_mov_b32_e32 v15, v0
	v_mov_b32_e32 v24, v0
	v_mov_b32_e32 v25, v0
	v_mov_b32_e32 v26, v0
	v_mov_b32_e32 v27, v0
	v_mov_b32_e32 v28, v0
	v_mov_b32_e32 v29, v0
	v_mov_b32_e32 v30, v0
	v_mov_b32_e32 v31, v0
	v_mov_b32_e32 v40, v0
	v_mov_b32_e32 v41, v0
	v_mov_b32_e32 v42, v0
	v_mov_b32_e32 v43, v0
	v_mov_b32_e32 v44, v0
	v_mov_b32_e32 v45, v0
	v_mov_b32_e32 v46, v0
	v_mov_b32_e32 v47, v0
	v_mov_b32_e32 v56, v0
	v_mov_b32_e32 v57, v0
	v_mov_b32_e32 v58, v0
	v_mov_b32_e32 v59, v0
	v_mov_b32_e32 v60, v0
	v_mov_b32_e32 v61, v0
	v_mov_b32_e32 v62, v0
	v_mov_b32_e32 v63, v0
	v_mov_b32_e32 v64, v0
	v_mov_b32_e32 v65, v0
	v_mov_b32_e32 v66, v0
	v_mov_b32_e32 v67, v0
	v_mov_b32_e32 v68, v0
	v_mov_b32_e32 v69, v0
	v_mov_b32_e32 v70, v0
	v_mov_b32_e32 v71, v0
	v_mov_b32_e32 v80, v0
	v_mov_b32_e32 v81, v0
	v_mov_b32_e32 v82, v0
	v_mov_b32_e32 v83, v0
	v_mov_b32_e32 v84, v0
	v_mov_b32_e32 v85, v0
	v_mov_b32_e32 v86, v0
	v_mov_b32_e32 v87, v0
	v_mov_b32_e32 v96, v0
	v_mov_b32_e32 v97, v0
	v_mov_b32_e32 v98, v0
	v_mov_b32_e32 v99, v0
	v_mov_b32_e32 v100, v0
	v_mov_b32_e32 v101, v0
	v_mov_b32_e32 v102, v0
	v_mov_b32_e32 v103, v0
	v_mov_b32_e32 v112, v0
	v_mov_b32_e32 v113, v0
	v_mov_b32_e32 v114, v0
	v_mov_b32_e32 v115, v0
	v_mov_b32_e32 v116, v0
	v_mov_b32_e32 v117, v0
	v_mov_b32_e32 v118, v0
	v_mov_b32_e32 v119, v0
	v_mov_b32_e32 v72, v0
	v_mov_b32_e32 v73, v0
	v_mov_b32_e32 v74, v0
	v_mov_b32_e32 v75, v0
	v_mov_b32_e32 v76, v0
	v_mov_b32_e32 v77, v0
	v_mov_b32_e32 v78, v0
	v_mov_b32_e32 v79, v0
	v_mov_b32_e32 v88, v0
	v_mov_b32_e32 v89, v0
	v_mov_b32_e32 v90, v0
	v_mov_b32_e32 v91, v0
	v_mov_b32_e32 v92, v0
	v_mov_b32_e32 v93, v0
	v_mov_b32_e32 v94, v0
	v_mov_b32_e32 v95, v0
	v_mov_b32_e32 v104, v0
	v_mov_b32_e32 v105, v0
	v_mov_b32_e32 v106, v0
	v_mov_b32_e32 v107, v0
	v_mov_b32_e32 v108, v0
	v_mov_b32_e32 v109, v0
	v_mov_b32_e32 v110, v0
	v_mov_b32_e32 v111, v0
	v_mov_b32_e32 v120, v0
	v_mov_b32_e32 v121, v0
	v_mov_b32_e32 v122, v0
	v_mov_b32_e32 v123, v0
	v_mov_b32_e32 v124, v0
	v_mov_b32_e32 v125, v0
	v_mov_b32_e32 v126, v0
	v_mov_b32_e32 v127, v0
	.p2align 6

; template <class Epi, class Sched, bool ALIGN_EPI = false, bool SP2 = false, bool F16 = false, bool TOKPERM = false>
; __device__ __forceinline__ void gemm_phase(PG8_LAS unsigned char* lds, const Gemm g, const Sched& S, const Epi& E, int wv) {
;     ...
;         const bool has_next = S.next(ui + 1, nxt);
;         const char* nA = has_next ? (const char*)g.A + (size_t)nxt.pm * tstep : cA; const char* nB = has_next ? (const char*)g.Bt + (size_t)nxt.pn * tstep : cB;
;     ...
; #pragma unroll
;         for (int a = 0; a < 2; ++a)
; #pragma unroll
;             for (int b = 0; b < 2; ++b)
; #pragma unroll
;                 for (int m = 0; m < 4; ++m)
; #pragma unroll
;                     for (int n = 0; n < 2; ++n) acc[a][b][m][n] = (f32x4){0.f, 0.f, 0.f, 0.f};
;         cur = nxt; cA = nA; cB = nB; ++ui;
.LBB0_1606:
	s_ashr_i32 s25, s24, 31
	s_lshl_b64 s[36:37], s[24:25], 19
	s_add_u32 s36, s40, s36
	s_addc_u32 s37, s41, s37
	s_and_b64 s[42:43], s[4:5], exec
	s_cselect_b32 s25, s37, s9
	s_cselect_b32 s64, s36, s8
	s_ashr_i32 s23, s22, 31
	s_lshl_b64 s[42:43], s[22:23], 19
	s_add_u32 s42, s0, s42
	s_addc_u32 s43, s1, s43
	s_and_b64 s[44:45], s[4:5], exec
	s_cselect_b32 s23, s43, s11
	s_cselect_b32 s65, s42, s10
	s_add_u32 s8, s8, 0x40080
	s_addc_u32 s9, s9, 0
	s_add_u32 s66, s10, 0x100
	v_mov_b32_e32 v0, 0
	s_addc_u32 s67, s11, 0
	s_mov_b32 s68, -2
	v_mov_b32_e32 v1, v0
	v_mov_b32_e32 v2, v0
	v_mov_b32_e32 v3, v0
	v_mov_b32_e32 v4, v0
	v_mov_b32_e32 v5, v0
	v_mov_b32_e32 v6, v0
	v_mov_b32_e32 v7, v0
	v_mov_b32_e32 v16, v0
	v_mov_b32_e32 v17, v0
	v_mov_b32_e32 v18, v0
	v_mov_b32_e32 v19, v0
	v_mov_b32_e32 v20, v0
	v_mov_b32_e32 v21, v0
	v_mov_b32_e32 v22, v0
	v_mov_b32_e32 v23, v0
	v_mov_b32_e32 v32, v0
	v_mov_b32_e32 v33, v0
	v_mov_b32_e32 v34, v0
	v_mov_b32_e32 v35, v0
	v_mov_b32_e32 v36, v0
	v_mov_b32_e32 v37, v0
	v_mov_b32_e32 v38, v0
	v_mov_b32_e32 v39, v0
	v_mov_b32_e32 v48, v0
	v_mov_b32_e32 v49, v0
	v_mov_b32_e32 v50, v0
	v_mov_b32_e32 v51, v0
	v_mov_b32_e32 v52, v0
	v_mov_b32_e32 v53, v0
	v_mov_b32_e32 v54, v0
	v_mov_b32_e32 v55, v0
	v_mov_b32_e32 v8, v0
	v_mov_b32_e32 v9, v0
	v_mov_b32_e32 v10, v0
	v_mov_b32_e32 v11, v0
	v_mov_b32_e32 v12, v0
	v_mov_b32_e32 v13, v0
	v_mov_b32_e32 v14, v0
	v_mov_b32_e32 v15, v0
	v_mov_b32_e32 v24, v0
	v_mov_b32_e32 v25, v0
	v_mov_b32_e32 v26, v0
	v_mov_b32_e32 v27, v0
	v_mov_b32_e32 v28, v0
	v_mov_b32_e32 v29, v0
	v_mov_b32_e32 v30, v0
	v_mov_b32_e32 v31, v0
	v_mov_b32_e32 v40, v0
	v_mov_b32_e32 v41, v0
	v_mov_b32_e32 v42, v0
	v_mov_b32_e32 v43, v0
	v_mov_b32_e32 v44, v0
	v_mov_b32_e32 v45, v0
	v_mov_b32_e32 v46, v0
	v_mov_b32_e32 v47, v0
	v_mov_b32_e32 v56, v0
	v_mov_b32_e32 v57, v0
	v_mov_b32_e32 v58, v0
	v_mov_b32_e32 v59, v0
	v_mov_b32_e32 v60, v0
	v_mov_b32_e32 v61, v0
	v_mov_b32_e32 v62, v0
	v_mov_b32_e32 v63, v0
	v_mov_b32_e32 v64, v0
	v_mov_b32_e32 v65, v0
	v_mov_b32_e32 v66, v0
	v_mov_b32_e32 v67, v0
	v_mov_b32_e32 v68, v0
	v_mov_b32_e32 v69, v0
	v_mov_b32_e32 v70, v0
	v_mov_b32_e32 v71, v0
	v_mov_b32_e32 v80, v0
	v_mov_b32_e32 v81, v0
	v_mov_b32_e32 v82, v0
	v_mov_b32_e32 v83, v0
	v_mov_b32_e32 v84, v0
	v_mov_b32_e32 v85, v0
	v_mov_b32_e32 v86, v0
	v_mov_b32_e32 v87, v0
	v_mov_b32_e32 v96, v0
	v_mov_b32_e32 v97, v0
	v_mov_b32_e32 v98, v0
	v_mov_b32_e32 v99, v0
	v_mov_b32_e32 v100, v0
	v_mov_b32_e32 v101, v0
	v_mov_b32_e32 v102, v0
	v_mov_b32_e32 v103, v0
	v_mov_b32_e32 v112, v0
	v_mov_b32_e32 v113, v0
	v_mov_b32_e32 v114, v0
	v_mov_b32_e32 v115, v0
	v_mov_b32_e32 v120, v0
	v_mov_b32_e32 v121, v0
	v_mov_b32_e32 v122, v0
	v_mov_b32_e32 v123, v0
	v_mov_b32_e32 v72, v0
	v_mov_b32_e32 v73, v0
	v_mov_b32_e32 v74, v0
	v_mov_b32_e32 v75, v0
	v_mov_b32_e32 v76, v0
	v_mov_b32_e32 v77, v0
	v_mov_b32_e32 v78, v0
	v_mov_b32_e32 v79, v0
	v_mov_b32_e32 v88, v0
	v_mov_b32_e32 v89, v0
	v_mov_b32_e32 v90, v0
	v_mov_b32_e32 v91, v0
	v_mov_b32_e32 v92, v0
	v_mov_b32_e32 v93, v0
	v_mov_b32_e32 v94, v0
	v_mov_b32_e32 v95, v0
	v_mov_b32_e32 v104, v0
	v_mov_b32_e32 v105, v0
	v_mov_b32_e32 v106, v0
	v_mov_b32_e32 v107, v0
	v_mov_b32_e32 v108, v0
	v_mov_b32_e32 v109, v0
	v_mov_b32_e32 v110, v0
	v_mov_b32_e32 v111, v0
	v_mov_b32_e32 v116, v0
	v_mov_b32_e32 v117, v0
	v_mov_b32_e32 v118, v0
	v_mov_b32_e32 v119, v0
	v_mov_b32_e32 v124, v0
	v_mov_b32_e32 v125, v0
	v_mov_b32_e32 v126, v0
	v_mov_b32_e32 v127, v0
	.p2align 6

; template <class Epi, class Sched, bool ALIGN_EPI = false, bool SP2 = false, bool F16 = false, bool TOKPERM = false>
; __device__ __forceinline__ void gemm_phase(PG8_LAS unsigned char* lds, const Gemm g, const Sched& S, const Epi& E, int wv) {
;     ...
; #pragma unroll
;         for (int a = 0; a < 2; ++a)
; #pragma unroll
;             for (int b = 0; b < 2; ++b)
; #pragma unroll
;                 for (int m = 0; m < 4; ++m)
; #pragma unroll
;                     for (int n = 0; n < 2; ++n) acc[a][b][m][n] = (f32x4){0.f, 0.f, 0.f, 0.f};
;         cur = nxt; cA = nA; cB = nB; ++ui;
.LBB0_1686:
	s_add_u32 s51, s10, 0x100
	v_mov_b32_e32 v0, 0
	s_addc_u32 s52, s11, 0
	s_mov_b32 s53, -2
	v_mov_b32_e32 v1, v0
	v_mov_b32_e32 v2, v0
	v_mov_b32_e32 v3, v0
	v_mov_b32_e32 v4, v0
	v_mov_b32_e32 v5, v0
	v_mov_b32_e32 v6, v0
	v_mov_b32_e32 v7, v0
	v_mov_b32_e32 v16, v0
	v_mov_b32_e32 v17, v0
	v_mov_b32_e32 v18, v0
	v_mov_b32_e32 v19, v0
	v_mov_b32_e32 v20, v0
	v_mov_b32_e32 v21, v0
	v_mov_b32_e32 v22, v0
	v_mov_b32_e32 v23, v0
	v_mov_b32_e32 v32, v0
	v_mov_b32_e32 v33, v0
	v_mov_b32_e32 v34, v0
	v_mov_b32_e32 v35, v0
	v_mov_b32_e32 v36, v0
	v_mov_b32_e32 v37, v0
	v_mov_b32_e32 v38, v0
	v_mov_b32_e32 v39, v0
	v_mov_b32_e32 v48, v0
	v_mov_b32_e32 v49, v0
	v_mov_b32_e32 v50, v0
	v_mov_b32_e32 v51, v0
	v_mov_b32_e32 v52, v0
	v_mov_b32_e32 v53, v0
	v_mov_b32_e32 v54, v0
	v_mov_b32_e32 v55, v0
	v_mov_b32_e32 v8, v0
	v_mov_b32_e32 v9, v0
	v_mov_b32_e32 v10, v0
	v_mov_b32_e32 v11, v0
	v_mov_b32_e32 v12, v0
	v_mov_b32_e32 v13, v0
	v_mov_b32_e32 v14, v0
	v_mov_b32_e32 v15, v0
	v_mov_b32_e32 v24, v0
	v_mov_b32_e32 v25, v0
	v_mov_b32_e32 v26, v0
	v_mov_b32_e32 v27, v0
	v_mov_b32_e32 v28, v0
	v_mov_b32_e32 v29, v0
	v_mov_b32_e32 v30, v0
	v_mov_b32_e32 v31, v0
	v_mov_b32_e32 v40, v0
	v_mov_b32_e32 v41, v0
	v_mov_b32_e32 v42, v0
	v_mov_b32_e32 v43, v0
	v_mov_b32_e32 v44, v0
	v_mov_b32_e32 v45, v0
	v_mov_b32_e32 v46, v0
	v_mov_b32_e32 v47, v0
	v_mov_b32_e32 v56, v0
	v_mov_b32_e32 v57, v0
	v_mov_b32_e32 v58, v0
	v_mov_b32_e32 v59, v0
	v_mov_b32_e32 v60, v0
	v_mov_b32_e32 v61, v0
	v_mov_b32_e32 v62, v0
	v_mov_b32_e32 v63, v0
	v_mov_b32_e32 v64, v0
	v_mov_b32_e32 v65, v0
	v_mov_b32_e32 v66, v0
	v_mov_b32_e32 v67, v0
	v_mov_b32_e32 v68, v0
	v_mov_b32_e32 v69, v0
	v_mov_b32_e32 v70, v0
	v_mov_b32_e32 v71, v0
	v_mov_b32_e32 v80, v0
	v_mov_b32_e32 v81, v0
	v_mov_b32_e32 v82, v0
	v_mov_b32_e32 v83, v0
	v_mov_b32_e32 v84, v0
	v_mov_b32_e32 v85, v0
	v_mov_b32_e32 v86, v0
	v_mov_b32_e32 v87, v0
	v_mov_b32_e32 v96, v0
	v_mov_b32_e32 v97, v0
	v_mov_b32_e32 v98, v0
	v_mov_b32_e32 v99, v0
	v_mov_b32_e32 v100, v0
	v_mov_b32_e32 v101, v0
	v_mov_b32_e32 v102, v0
	v_mov_b32_e32 v103, v0
	v_mov_b32_e32 v112, v0
	v_mov_b32_e32 v113, v0
	v_mov_b32_e32 v114, v0
	v_mov_b32_e32 v115, v0
	v_mov_b32_e32 v116, v0
	v_mov_b32_e32 v117, v0
	v_mov_b32_e32 v118, v0
	v_mov_b32_e32 v119, v0
	v_mov_b32_e32 v72, v0
	v_mov_b32_e32 v73, v0
	v_mov_b32_e32 v74, v0
	v_mov_b32_e32 v75, v0
	v_mov_b32_e32 v76, v0
	v_mov_b32_e32 v77, v0
	v_mov_b32_e32 v78, v0
	v_mov_b32_e32 v79, v0
	v_mov_b32_e32 v88, v0
	v_mov_b32_e32 v89, v0
	v_mov_b32_e32 v90, v0
	v_mov_b32_e32 v91, v0
	v_mov_b32_e32 v92, v0
	v_mov_b32_e32 v93, v0
	v_mov_b32_e32 v94, v0
	v_mov_b32_e32 v95, v0
	v_mov_b32_e32 v104, v0
	v_mov_b32_e32 v105, v0
	v_mov_b32_e32 v106, v0
	v_mov_b32_e32 v107, v0
	v_mov_b32_e32 v108, v0
	v_mov_b32_e32 v109, v0
	v_mov_b32_e32 v110, v0
	v_mov_b32_e32 v111, v0
	v_mov_b32_e32 v120, v0
	v_mov_b32_e32 v121, v0
	v_mov_b32_e32 v122, v0
	v_mov_b32_e32 v123, v0
	v_mov_b32_e32 v124, v0
	v_mov_b32_e32 v125, v0
	v_mov_b32_e32 v126, v0
	v_mov_b32_e32 v127, v0
	.p2align 6
